# hazard padding restored at 4 spots (wait states that the removed s_setprio / folded address adds used to provide); otherwise identical to the barrier-broadcast version
# baseline (speedup 1.0000x reference)
.LBB0_853:
	s_ashr_i32 s19, s18, 31
	s_lshl_b64 s[22:23], s[18:19], 18
	s_add_u32 s22, s30, s22
	s_addc_u32 s23, s31, s23
	s_and_b64 s[0:1], s[0:1], exec
	s_cselect_b32 s1, s23, s25
	s_cselect_b32 s0, s22, s24
	s_add_i32 s50, 0, 0x10000
	s_add_i32 s51, 0, 0x14000
	v_add_u32_e32 v8, s50, v138
	v_add_u32_e32 v9, s51, v138
	ds_read_b128 v[10:13], v8
	ds_read_b128 v[14:17], v8 offset:1024
	ds_read_b128 v[18:21], v8 offset:2048
	ds_read_b128 v[22:25], v8 offset:3072
	ds_read_b128 v[26:29], v9
	ds_read_b128 v[30:33], v9 offset:1024
	ds_read_b128 v[34:37], v9 offset:2048
	ds_read_b128 v[38:41], v9 offset:3072
	s_add_u32 s48, s24, 0x20080
	s_addc_u32 s49, s25, 0
	s_add_i32 s53, s36, 0xc000
	v_lshl_add_u64 v[66:67], s[48:49], 0, v[132:133]
	s_mov_b32 m0, s53
	s_add_i32 s19, s36, 0xe000
	ds_read_b128 v[0:3], v139
	ds_read_b128 v[4:7], v139 offset:1024
	ds_read_b128 v[42:45], v139 offset:2048
	ds_read_b128 v[46:49], v139 offset:3072
	ds_read_b128 v[50:53], v139 offset:4096
	ds_read_b128 v[54:57], v139 offset:5120
	ds_read_b128 v[58:61], v139 offset:6144
	ds_read_b128 v[62:65], v139 offset:7168
	global_load_lds_dwordx4 v[66:67], off
	v_lshl_add_u64 v[66:67], s[48:49], 0, v[130:131]
	s_mov_b32 m0, s19
	s_nop 0
	global_load_lds_dwordx4 v[66:67], off
	s_waitcnt vmcnt(8)
	s_waitcnt lgkmcnt(0)
	s_barrier
	s_waitcnt lgkmcnt(0)
	v_mfma_f32_16x16x32_bf16 v[66:69], v[10:13], v[0:3], 0
	v_mfma_f32_16x16x32_bf16 v[70:73], v[18:21], v[0:3], 0
	v_mfma_f32_16x16x32_bf16 v[74:77], v[10:13], v[42:45], 0
	v_mfma_f32_16x16x32_bf16 v[78:81], v[18:21], v[42:45], 0
	v_mfma_f32_16x16x32_bf16 v[82:85], v[10:13], v[50:53], 0
	v_mfma_f32_16x16x32_bf16 v[86:89], v[18:21], v[50:53], 0
	v_mfma_f32_16x16x32_bf16 v[90:93], v[10:13], v[58:61], 0
	v_mfma_f32_16x16x32_bf16 v[94:97], v[18:21], v[58:61], 0
	v_mfma_f32_16x16x32_bf16 v[66:69], v[14:17], v[4:7], v[66:69]
	v_mfma_f32_16x16x32_bf16 v[70:73], v[22:25], v[4:7], v[70:73]
	v_mfma_f32_16x16x32_bf16 v[74:77], v[14:17], v[46:49], v[74:77]
	v_mfma_f32_16x16x32_bf16 v[78:81], v[22:25], v[46:49], v[78:81]
	v_mfma_f32_16x16x32_bf16 v[82:85], v[14:17], v[54:57], v[82:85]
	v_mfma_f32_16x16x32_bf16 v[86:89], v[22:25], v[54:57], v[86:89]
	v_mfma_f32_16x16x32_bf16 v[90:93], v[14:17], v[62:65], v[90:93]
	v_mfma_f32_16x16x32_bf16 v[94:97], v[22:25], v[62:65], v[94:97]
	v_mfma_f32_16x16x32_bf16 v[98:101], v[26:29], v[0:3], 0
	v_mfma_f32_16x16x32_bf16 v[0:3], v[34:37], v[0:3], 0
	v_mfma_f32_16x16x32_bf16 v[102:105], v[38:41], v[4:7], v[0:3]
	v_mfma_f32_16x16x32_bf16 v[0:3], v[26:29], v[42:45], 0
	v_mfma_f32_16x16x32_bf16 v[106:109], v[30:33], v[46:49], v[0:3]
	v_mfma_f32_16x16x32_bf16 v[0:3], v[34:37], v[42:45], 0
	v_mfma_f32_16x16x32_bf16 v[42:45], v[38:41], v[46:49], v[0:3]
	v_mfma_f32_16x16x32_bf16 v[0:3], v[26:29], v[50:53], 0
	v_mfma_f32_16x16x32_bf16 v[46:49], v[30:33], v[54:57], v[0:3]
	v_mfma_f32_16x16x32_bf16 v[0:3], v[34:37], v[50:53], 0
	v_mfma_f32_16x16x32_bf16 v[50:53], v[38:41], v[54:57], v[0:3]
	v_mfma_f32_16x16x32_bf16 v[0:3], v[26:29], v[58:61], 0
	v_mfma_f32_16x16x32_bf16 v[54:57], v[30:33], v[62:65], v[0:3]
	v_mfma_f32_16x16x32_bf16 v[0:3], v[34:37], v[58:61], 0
	v_mfma_f32_16x16x32_bf16 v[98:101], v[30:33], v[4:7], v[98:101]
	v_mfma_f32_16x16x32_bf16 v[58:61], v[38:41], v[62:65], v[0:3]
	s_barrier
	s_nop 4
	v_lshl_add_u64 v[0:1], s[26:27], 0, v[148:149]
	s_mov_b64 s[56:57], 0x100
	s_add_i32 s50, s50, s35
	v_lshl_add_u64 v[2:3], v[0:1], 0, s[56:57]
	s_mov_b32 m0, s50
	s_add_i32 s47, s50, 0x2000
	ds_read_b128 v[62:65], v139 offset:16384
	ds_read_b128 v[110:113], v139 offset:17408
	ds_read_b128 v[114:117], v139 offset:18432
	ds_read_b128 v[118:121], v139 offset:19456
	ds_read_b128 v[122:125], v139 offset:20480
	ds_read_b128 v[134:137], v139 offset:21504
	ds_read_b128 v[140:143], v139 offset:22528
	ds_read_b128 v[144:147], v139 offset:23552
	global_load_lds_dwordx4 v[2:3], off
	v_lshl_add_u64 v[2:3], s[26:27], 0, v[128:129]
	s_add_u32 s54, s26, 0x18100
	v_lshl_add_u64 v[4:5], v[2:3], 0, s[56:57]
	s_mov_b32 m0, s47
	s_addc_u32 s55, s27, 0
	s_add_i32 s48, s51, s35
	global_load_lds_dwordx4 v[4:5], off
	v_lshl_add_u64 v[4:5], s[54:55], 0, v[148:149]
	s_mov_b32 m0, s48
	s_add_i32 s49, s48, 0x2000
	global_load_lds_dwordx4 v[4:5], off
	v_lshl_add_u64 v[4:5], s[54:55], 0, v[128:129]
	s_mov_b32 m0, s49
	s_nop 0
	global_load_lds_dwordx4 v[4:5], off
	v_lshl_add_u64 v[4:5], s[24:25], 0, v[132:133]
	v_lshl_add_u64 v[6:7], v[4:5], 0, s[56:57]
	s_mov_b32 m0, s36
	s_nop 0
	global_load_lds_dwordx4 v[6:7], off
	v_lshl_add_u64 v[6:7], s[24:25], 0, v[130:131]
	v_lshl_add_u64 v[126:127], v[6:7], 0, s[56:57]
	s_mov_b32 m0, s37
	s_nop 0
	global_load_lds_dwordx4 v[126:127], off
	s_waitcnt vmcnt(8)
	s_waitcnt lgkmcnt(0)
	s_barrier
	s_waitcnt lgkmcnt(0)
	v_mfma_f32_16x16x32_bf16 v[158:161], v[10:13], v[62:65], 0
	v_mfma_f32_16x16x32_bf16 v[166:169], v[10:13], v[114:117], 0
	v_mfma_f32_16x16x32_bf16 v[174:177], v[10:13], v[122:125], 0
	v_mfma_f32_16x16x32_bf16 v[10:13], v[10:13], v[140:143], 0
	v_mfma_f32_16x16x32_bf16 v[158:161], v[14:17], v[110:113], v[158:161]
	v_mfma_f32_16x16x32_bf16 v[162:165], v[18:21], v[62:65], 0
	v_mfma_f32_16x16x32_bf16 v[166:169], v[14:17], v[118:121], v[166:169]
	v_mfma_f32_16x16x32_bf16 v[170:173], v[18:21], v[114:117], 0
	v_mfma_f32_16x16x32_bf16 v[174:177], v[14:17], v[134:137], v[174:177]
	v_mfma_f32_16x16x32_bf16 v[178:181], v[18:21], v[122:125], 0
	v_mfma_f32_16x16x32_bf16 v[12:15], v[14:17], v[144:147], v[10:13]
	v_mfma_f32_16x16x32_bf16 v[16:19], v[18:21], v[140:143], 0
	v_mfma_f32_16x16x32_bf16 v[16:19], v[22:25], v[144:147], v[16:19]
	v_mfma_f32_16x16x32_bf16 v[162:165], v[22:25], v[110:113], v[162:165]
	v_mfma_f32_16x16x32_bf16 v[170:173], v[22:25], v[118:121], v[170:173]
	v_mfma_f32_16x16x32_bf16 v[178:181], v[22:25], v[134:137], v[178:181]
	v_mfma_f32_16x16x32_bf16 v[20:23], v[26:29], v[62:65], 0
	v_mfma_f32_16x16x32_bf16 v[62:65], v[34:37], v[62:65], 0
	v_mfma_f32_16x16x32_bf16 v[20:23], v[30:33], v[110:113], v[20:23]
	v_mfma_f32_16x16x32_bf16 v[62:65], v[38:41], v[110:113], v[62:65]
	v_mfma_f32_16x16x32_bf16 v[110:113], v[26:29], v[114:117], 0
	v_mfma_f32_16x16x32_bf16 v[114:117], v[34:37], v[114:117], 0
	v_mfma_f32_16x16x32_bf16 v[110:113], v[30:33], v[118:121], v[110:113]
	v_mfma_f32_16x16x32_bf16 v[114:117], v[38:41], v[118:121], v[114:117]
	v_mfma_f32_16x16x32_bf16 v[118:121], v[26:29], v[122:125], 0
	v_mfma_f32_16x16x32_bf16 v[24:27], v[26:29], v[140:143], 0
	v_mfma_f32_16x16x32_bf16 v[118:121], v[30:33], v[134:137], v[118:121]
	v_mfma_f32_16x16x32_bf16 v[122:125], v[34:37], v[122:125], 0
	v_mfma_f32_16x16x32_bf16 v[24:27], v[30:33], v[144:147], v[24:27]
	v_mfma_f32_16x16x32_bf16 v[28:31], v[34:37], v[140:143], 0
	v_mfma_f32_16x16x32_bf16 v[122:125], v[38:41], v[134:137], v[122:125]
	v_mfma_f32_16x16x32_bf16 v[28:31], v[38:41], v[144:147], v[28:31]
	s_barrier
	s_add_i32 s51, 0, 0x18000
	s_add_i32 s52, 0, 0x1c000
	v_add_u32_e32 v10, s51, v138
	v_add_u32_e32 v11, s52, v138
	ds_read_b128 v[32:35], v10
	ds_read_b128 v[36:39], v10 offset:1024
	ds_read_b128 v[134:137], v10 offset:2048
	ds_read_b128 v[140:143], v10 offset:3072
	ds_read_b128 v[144:147], v11
	ds_read_b128 v[182:185], v11 offset:1024
	ds_read_b128 v[186:189], v11 offset:2048
	ds_read_b128 v[190:193], v11 offset:3072
	s_add_u32 s54, s24, 0x20100
	s_addc_u32 s55, s25, 0
	s_mov_b32 m0, s38
	v_lshl_add_u64 v[40:41], s[54:55], 0, v[132:133]
	ds_read_b128 v[194:197], v139 offset:32768
	ds_read_b128 v[198:201], v139 offset:33792
	ds_read_b128 v[202:205], v139 offset:34816
	ds_read_b128 v[218:221], v139 offset:35840
	ds_read_b128 v[222:225], v139 offset:36864
	ds_read_b128 v[226:229], v139 offset:37888
	ds_read_b128 v[230:233], v139 offset:38912
	ds_read_b128 v[234:237], v139 offset:39936
	global_load_lds_dwordx4 v[40:41], off
	v_lshl_add_u64 v[40:41], s[54:55], 0, v[130:131]
	s_mov_b32 m0, s39
	s_nop 0
	global_load_lds_dwordx4 v[40:41], off
	s_waitcnt vmcnt(8)
	s_waitcnt lgkmcnt(0)
	s_barrier
	s_waitcnt lgkmcnt(0)
	v_mfma_f32_16x16x32_bf16 v[66:69], v[32:35], v[194:197], v[66:69]
	v_mfma_f32_16x16x32_bf16 v[70:73], v[134:137], v[194:197], v[70:73]
	v_mfma_f32_16x16x32_bf16 v[74:77], v[32:35], v[202:205], v[74:77]
	v_mfma_f32_16x16x32_bf16 v[78:81], v[134:137], v[202:205], v[78:81]
	v_mfma_f32_16x16x32_bf16 v[82:85], v[32:35], v[222:225], v[82:85]
	v_mfma_f32_16x16x32_bf16 v[86:89], v[134:137], v[222:225], v[86:89]
	v_mfma_f32_16x16x32_bf16 v[90:93], v[32:35], v[230:233], v[90:93]
	v_mfma_f32_16x16x32_bf16 v[94:97], v[134:137], v[230:233], v[94:97]
	v_mfma_f32_16x16x32_bf16 v[66:69], v[36:39], v[198:201], v[66:69]
	v_mfma_f32_16x16x32_bf16 v[70:73], v[140:143], v[198:201], v[70:73]
	v_mfma_f32_16x16x32_bf16 v[74:77], v[36:39], v[218:221], v[74:77]
	v_mfma_f32_16x16x32_bf16 v[78:81], v[140:143], v[218:221], v[78:81]
	v_mfma_f32_16x16x32_bf16 v[82:85], v[36:39], v[226:229], v[82:85]
	v_mfma_f32_16x16x32_bf16 v[86:89], v[140:143], v[226:229], v[86:89]
	v_mfma_f32_16x16x32_bf16 v[90:93], v[36:39], v[234:237], v[90:93]
	v_mfma_f32_16x16x32_bf16 v[94:97], v[140:143], v[234:237], v[94:97]
	v_mfma_f32_16x16x32_bf16 v[98:101], v[144:147], v[194:197], v[98:101]
	v_mfma_f32_16x16x32_bf16 v[102:105], v[186:189], v[194:197], v[102:105]
	v_mfma_f32_16x16x32_bf16 v[106:109], v[144:147], v[202:205], v[106:109]
	v_mfma_f32_16x16x32_bf16 v[40:43], v[186:189], v[202:205], v[42:45]
	v_mfma_f32_16x16x32_bf16 v[44:47], v[144:147], v[222:225], v[46:49]
	v_mfma_f32_16x16x32_bf16 v[48:51], v[186:189], v[222:225], v[50:53]
	v_mfma_f32_16x16x32_bf16 v[52:55], v[144:147], v[230:233], v[54:57]
	v_mfma_f32_16x16x32_bf16 v[56:59], v[186:189], v[230:233], v[58:61]
	v_mfma_f32_16x16x32_bf16 v[98:101], v[182:185], v[198:201], v[98:101]
	v_mfma_f32_16x16x32_bf16 v[102:105], v[190:193], v[198:201], v[102:105]
	v_mfma_f32_16x16x32_bf16 v[106:109], v[182:185], v[218:221], v[106:109]
	v_mfma_f32_16x16x32_bf16 v[40:43], v[190:193], v[218:221], v[40:43]
	v_mfma_f32_16x16x32_bf16 v[44:47], v[182:185], v[226:229], v[44:47]
	v_mfma_f32_16x16x32_bf16 v[48:51], v[190:193], v[226:229], v[48:51]
	v_mfma_f32_16x16x32_bf16 v[52:55], v[182:185], v[234:237], v[52:55]
	v_mfma_f32_16x16x32_bf16 v[56:59], v[190:193], v[234:237], v[56:59]
	s_barrier
	s_add_i32 s55, s51, s35
	s_mov_b64 s[60:61], 0x180
	s_add_i32 s51, s55, 0x2000
	v_lshl_add_u64 v[60:61], v[0:1], 0, s[60:61]
	s_mov_b32 m0, s55
	s_add_u32 s56, s26, 0x18180
	ds_read_b128 v[194:197], v139 offset:49152
	ds_read_b128 v[198:201], v139 offset:50176
	ds_read_b128 v[202:205], v139 offset:51200
	ds_read_b128 v[218:221], v139 offset:52224
	ds_read_b128 v[222:225], v139 offset:53248
	ds_read_b128 v[226:229], v139 offset:54272
	ds_read_b128 v[230:233], v139 offset:55296
	ds_read_b128 v[234:237], v139 offset:56320
	global_load_lds_dwordx4 v[60:61], off
	v_lshl_add_u64 v[60:61], v[2:3], 0, s[60:61]
	s_mov_b32 m0, s51
	s_addc_u32 s57, s27, 0
	s_add_i32 s52, s52, s35
	global_load_lds_dwordx4 v[60:61], off
	v_lshl_add_u64 v[60:61], s[56:57], 0, v[148:149]
	s_mov_b32 m0, s52
	s_add_i32 s54, s52, 0x2000
	global_load_lds_dwordx4 v[60:61], off
	v_lshl_add_u64 v[60:61], s[56:57], 0, v[128:129]
	s_mov_b32 m0, s54
	s_nop 0
	global_load_lds_dwordx4 v[60:61], off
	v_lshl_add_u64 v[60:61], v[4:5], 0, s[60:61]
	s_mov_b32 m0, s42
	s_nop 0
	global_load_lds_dwordx4 v[60:61], off
	v_lshl_add_u64 v[60:61], v[6:7], 0, s[60:61]
	s_mov_b32 m0, s43
	s_nop 0
	global_load_lds_dwordx4 v[60:61], off
	s_waitcnt vmcnt(8)
	s_waitcnt lgkmcnt(0)
	s_barrier
	s_waitcnt lgkmcnt(0)
	v_mfma_f32_16x16x32_bf16 v[12:15], v[32:35], v[230:233], v[12:15]
	v_mfma_f32_16x16x32_bf16 v[16:19], v[134:137], v[230:233], v[16:19]
	v_mfma_f32_16x16x32_bf16 v[158:161], v[32:35], v[194:197], v[158:161]
	v_mfma_f32_16x16x32_bf16 v[162:165], v[134:137], v[194:197], v[162:165]
	v_mfma_f32_16x16x32_bf16 v[166:169], v[32:35], v[202:205], v[166:169]
	v_mfma_f32_16x16x32_bf16 v[170:173], v[134:137], v[202:205], v[170:173]
	v_mfma_f32_16x16x32_bf16 v[174:177], v[32:35], v[222:225], v[174:177]
	v_mfma_f32_16x16x32_bf16 v[178:181], v[134:137], v[222:225], v[178:181]
	v_mfma_f32_16x16x32_bf16 v[12:15], v[36:39], v[234:237], v[12:15]
	v_mfma_f32_16x16x32_bf16 v[16:19], v[140:143], v[234:237], v[16:19]
	v_mfma_f32_16x16x32_bf16 v[158:161], v[36:39], v[198:201], v[158:161]
	v_mfma_f32_16x16x32_bf16 v[162:165], v[140:143], v[198:201], v[162:165]
	v_mfma_f32_16x16x32_bf16 v[166:169], v[36:39], v[218:221], v[166:169]
	v_mfma_f32_16x16x32_bf16 v[170:173], v[140:143], v[218:221], v[170:173]
	v_mfma_f32_16x16x32_bf16 v[174:177], v[36:39], v[226:229], v[174:177]
	v_mfma_f32_16x16x32_bf16 v[178:181], v[140:143], v[226:229], v[178:181]
	v_mfma_f32_16x16x32_bf16 v[20:23], v[144:147], v[194:197], v[20:23]
	v_mfma_f32_16x16x32_bf16 v[32:35], v[186:189], v[194:197], v[62:65]
	v_mfma_f32_16x16x32_bf16 v[36:39], v[144:147], v[202:205], v[110:113]
	v_mfma_f32_16x16x32_bf16 v[60:63], v[186:189], v[202:205], v[114:117]
	v_mfma_f32_16x16x32_bf16 v[110:113], v[144:147], v[222:225], v[118:121]
	v_mfma_f32_16x16x32_bf16 v[114:117], v[186:189], v[222:225], v[122:125]
	v_mfma_f32_16x16x32_bf16 v[24:27], v[144:147], v[230:233], v[24:27]
	v_mfma_f32_16x16x32_bf16 v[28:31], v[186:189], v[230:233], v[28:31]
	v_mfma_f32_16x16x32_bf16 v[20:23], v[182:185], v[198:201], v[20:23]
	v_mfma_f32_16x16x32_bf16 v[32:35], v[190:193], v[198:201], v[32:35]
	v_mfma_f32_16x16x32_bf16 v[36:39], v[182:185], v[218:221], v[36:39]
	v_mfma_f32_16x16x32_bf16 v[60:63], v[190:193], v[218:221], v[60:63]
	v_mfma_f32_16x16x32_bf16 v[110:113], v[182:185], v[226:229], v[110:113]
	v_mfma_f32_16x16x32_bf16 v[114:117], v[190:193], v[226:229], v[114:117]
	v_mfma_f32_16x16x32_bf16 v[24:27], v[182:185], v[234:237], v[24:27]
	v_mfma_f32_16x16x32_bf16 v[28:31], v[190:193], v[234:237], v[28:31]
	s_barrier
	ds_read_b128 v[118:121], v8
	ds_read_b128 v[122:125], v8 offset:1024
	ds_read_b128 v[134:137], v8 offset:2048
	ds_read_b128 v[140:143], v8 offset:3072
	ds_read_b128 v[144:147], v9
	ds_read_b128 v[182:185], v9 offset:1024
	ds_read_b128 v[186:189], v9 offset:2048
	ds_read_b128 v[190:193], v9 offset:3072
	s_add_u32 s56, s24, 0x20180
	s_addc_u32 s57, s25, 0
	s_mov_b32 m0, s53
	v_lshl_add_u64 v[64:65], s[56:57], 0, v[132:133]
	ds_read_b128 v[194:197], v139
	ds_read_b128 v[198:201], v139 offset:1024
	ds_read_b128 v[202:205], v139 offset:2048
	ds_read_b128 v[218:221], v139 offset:3072
	ds_read_b128 v[222:225], v139 offset:4096
	ds_read_b128 v[226:229], v139 offset:5120
	ds_read_b128 v[230:233], v139 offset:6144
	ds_read_b128 v[234:237], v139 offset:7168
	global_load_lds_dwordx4 v[64:65], off
	v_lshl_add_u64 v[64:65], s[56:57], 0, v[130:131]
	s_mov_b32 m0, s19
	s_nop 0
	global_load_lds_dwordx4 v[64:65], off
	s_waitcnt vmcnt(8)
	s_waitcnt lgkmcnt(0)
	s_barrier
	s_waitcnt lgkmcnt(0)
	v_mfma_f32_16x16x32_bf16 v[64:67], v[118:121], v[194:197], v[66:69]
	v_mfma_f32_16x16x32_bf16 v[68:71], v[134:137], v[194:197], v[70:73]
	v_mfma_f32_16x16x32_bf16 v[72:75], v[118:121], v[202:205], v[74:77]
	v_mfma_f32_16x16x32_bf16 v[76:79], v[134:137], v[202:205], v[78:81]
	v_mfma_f32_16x16x32_bf16 v[80:83], v[118:121], v[222:225], v[82:85]
	v_mfma_f32_16x16x32_bf16 v[84:87], v[134:137], v[222:225], v[86:89]
	v_mfma_f32_16x16x32_bf16 v[88:91], v[118:121], v[230:233], v[90:93]
	v_mfma_f32_16x16x32_bf16 v[92:95], v[134:137], v[230:233], v[94:97]
	v_mfma_f32_16x16x32_bf16 v[64:67], v[122:125], v[198:201], v[64:67]
	v_mfma_f32_16x16x32_bf16 v[68:71], v[140:143], v[198:201], v[68:71]
	v_mfma_f32_16x16x32_bf16 v[72:75], v[122:125], v[218:221], v[72:75]
	v_mfma_f32_16x16x32_bf16 v[76:79], v[140:143], v[218:221], v[76:79]
	v_mfma_f32_16x16x32_bf16 v[80:83], v[122:125], v[226:229], v[80:83]
	v_mfma_f32_16x16x32_bf16 v[84:87], v[140:143], v[226:229], v[84:87]
	v_mfma_f32_16x16x32_bf16 v[88:91], v[122:125], v[234:237], v[88:91]
	v_mfma_f32_16x16x32_bf16 v[92:95], v[140:143], v[234:237], v[92:95]
	v_mfma_f32_16x16x32_bf16 v[96:99], v[144:147], v[194:197], v[98:101]
	v_mfma_f32_16x16x32_bf16 v[100:103], v[186:189], v[194:197], v[102:105]
	v_mfma_f32_16x16x32_bf16 v[104:107], v[144:147], v[202:205], v[106:109]
	v_mfma_f32_16x16x32_bf16 v[40:43], v[186:189], v[202:205], v[40:43]
	v_mfma_f32_16x16x32_bf16 v[44:47], v[144:147], v[222:225], v[44:47]
	v_mfma_f32_16x16x32_bf16 v[48:51], v[186:189], v[222:225], v[48:51]
	v_mfma_f32_16x16x32_bf16 v[52:55], v[144:147], v[230:233], v[52:55]
	v_mfma_f32_16x16x32_bf16 v[56:59], v[186:189], v[230:233], v[56:59]
	v_mfma_f32_16x16x32_bf16 v[96:99], v[182:185], v[198:201], v[96:99]
	v_mfma_f32_16x16x32_bf16 v[100:103], v[190:193], v[198:201], v[100:103]
	v_mfma_f32_16x16x32_bf16 v[104:107], v[182:185], v[218:221], v[104:107]
	v_mfma_f32_16x16x32_bf16 v[40:43], v[190:193], v[218:221], v[40:43]
	v_mfma_f32_16x16x32_bf16 v[44:47], v[182:185], v[226:229], v[44:47]
	v_mfma_f32_16x16x32_bf16 v[48:51], v[190:193], v[226:229], v[48:51]
	v_mfma_f32_16x16x32_bf16 v[52:55], v[182:185], v[234:237], v[52:55]
	v_mfma_f32_16x16x32_bf16 v[56:59], v[190:193], v[234:237], v[56:59]
	s_barrier
	s_mov_b64 s[60:61], 0x200
	s_mov_b32 m0, s50
	v_lshl_add_u64 v[108:109], v[0:1], 0, s[60:61]
	s_add_u32 s56, s26, 0x18200
	ds_read_b128 v[194:197], v139 offset:16384
	ds_read_b128 v[198:201], v139 offset:17408
	ds_read_b128 v[202:205], v139 offset:18432
	ds_read_b128 v[218:221], v139 offset:19456
	ds_read_b128 v[222:225], v139 offset:20480
	ds_read_b128 v[226:229], v139 offset:21504
	ds_read_b128 v[230:233], v139 offset:22528
	ds_read_b128 v[234:237], v139 offset:23552
	global_load_lds_dwordx4 v[108:109], off
	v_lshl_add_u64 v[108:109], v[2:3], 0, s[60:61]
	s_mov_b32 m0, s47
	s_addc_u32 s57, s27, 0
	global_load_lds_dwordx4 v[108:109], off
	v_lshl_add_u64 v[108:109], s[56:57], 0, v[148:149]
	s_mov_b32 m0, s48
	s_nop 0
	global_load_lds_dwordx4 v[108:109], off
	v_lshl_add_u64 v[108:109], s[56:57], 0, v[128:129]
	s_mov_b32 m0, s49
	s_nop 0
	global_load_lds_dwordx4 v[108:109], off
	v_lshl_add_u64 v[108:109], v[4:5], 0, s[60:61]
	s_mov_b32 m0, s36
	s_nop 0
	global_load_lds_dwordx4 v[108:109], off
	v_lshl_add_u64 v[108:109], v[6:7], 0, s[60:61]
	s_mov_b32 m0, s37
	s_nop 0
	global_load_lds_dwordx4 v[108:109], off
	s_waitcnt vmcnt(8)
	s_waitcnt lgkmcnt(0)
	s_barrier
	s_waitcnt lgkmcnt(0)
	v_mfma_f32_16x16x32_bf16 v[12:15], v[118:121], v[230:233], v[12:15]
	v_mfma_f32_16x16x32_bf16 v[16:19], v[134:137], v[230:233], v[16:19]
	v_mfma_f32_16x16x32_bf16 v[158:161], v[118:121], v[194:197], v[158:161]
	v_mfma_f32_16x16x32_bf16 v[162:165], v[134:137], v[194:197], v[162:165]
	v_mfma_f32_16x16x32_bf16 v[166:169], v[118:121], v[202:205], v[166:169]
	v_mfma_f32_16x16x32_bf16 v[170:173], v[134:137], v[202:205], v[170:173]
	v_mfma_f32_16x16x32_bf16 v[174:177], v[118:121], v[222:225], v[174:177]
	v_mfma_f32_16x16x32_bf16 v[178:181], v[134:137], v[222:225], v[178:181]
	v_mfma_f32_16x16x32_bf16 v[12:15], v[122:125], v[234:237], v[12:15]
	v_mfma_f32_16x16x32_bf16 v[16:19], v[140:143], v[234:237], v[16:19]
	v_mfma_f32_16x16x32_bf16 v[158:161], v[122:125], v[198:201], v[158:161]
	v_mfma_f32_16x16x32_bf16 v[162:165], v[140:143], v[198:201], v[162:165]
	v_mfma_f32_16x16x32_bf16 v[166:169], v[122:125], v[218:221], v[166:169]
	v_mfma_f32_16x16x32_bf16 v[170:173], v[140:143], v[218:221], v[170:173]
	v_mfma_f32_16x16x32_bf16 v[174:177], v[122:125], v[226:229], v[174:177]
	v_mfma_f32_16x16x32_bf16 v[178:181], v[140:143], v[226:229], v[178:181]
	v_mfma_f32_16x16x32_bf16 v[20:23], v[144:147], v[194:197], v[20:23]
	v_mfma_f32_16x16x32_bf16 v[32:35], v[186:189], v[194:197], v[32:35]
	v_mfma_f32_16x16x32_bf16 v[36:39], v[144:147], v[202:205], v[36:39]
	v_mfma_f32_16x16x32_bf16 v[60:63], v[186:189], v[202:205], v[60:63]
	v_mfma_f32_16x16x32_bf16 v[108:111], v[144:147], v[222:225], v[110:113]
	v_mfma_f32_16x16x32_bf16 v[112:115], v[186:189], v[222:225], v[114:117]
	v_mfma_f32_16x16x32_bf16 v[24:27], v[144:147], v[230:233], v[24:27]
	v_mfma_f32_16x16x32_bf16 v[28:31], v[186:189], v[230:233], v[28:31]
	v_mfma_f32_16x16x32_bf16 v[20:23], v[182:185], v[198:201], v[20:23]
	v_mfma_f32_16x16x32_bf16 v[32:35], v[190:193], v[198:201], v[32:35]
	v_mfma_f32_16x16x32_bf16 v[36:39], v[182:185], v[218:221], v[36:39]
	v_mfma_f32_16x16x32_bf16 v[60:63], v[190:193], v[218:221], v[60:63]
	v_mfma_f32_16x16x32_bf16 v[108:111], v[182:185], v[226:229], v[108:111]
	v_mfma_f32_16x16x32_bf16 v[112:115], v[190:193], v[226:229], v[112:115]
	v_mfma_f32_16x16x32_bf16 v[24:27], v[182:185], v[234:237], v[24:27]
	v_mfma_f32_16x16x32_bf16 v[28:31], v[190:193], v[234:237], v[28:31]
	s_barrier
	ds_read_b128 v[116:119], v10
	ds_read_b128 v[120:123], v10 offset:1024
	ds_read_b128 v[124:127], v10 offset:2048
	ds_read_b128 v[134:137], v10 offset:3072
	ds_read_b128 v[140:143], v11
	ds_read_b128 v[144:147], v11 offset:1024
	ds_read_b128 v[182:185], v11 offset:2048
	ds_read_b128 v[186:189], v11 offset:3072
	s_add_u32 s56, s24, 0x20200
	s_addc_u32 s57, s25, 0
	s_mov_b32 m0, s38
	v_lshl_add_u64 v[154:155], s[56:57], 0, v[132:133]
	ds_read_b128 v[190:193], v139 offset:32768
	ds_read_b128 v[194:197], v139 offset:33792
	ds_read_b128 v[198:201], v139 offset:34816
	ds_read_b128 v[202:205], v139 offset:35840
	ds_read_b128 v[218:221], v139 offset:36864
	ds_read_b128 v[222:225], v139 offset:37888
	ds_read_b128 v[226:229], v139 offset:38912
	ds_read_b128 v[230:233], v139 offset:39936
	global_load_lds_dwordx4 v[154:155], off
	v_lshl_add_u64 v[154:155], s[56:57], 0, v[130:131]
	s_mov_b32 m0, s39
	s_nop 0
	global_load_lds_dwordx4 v[154:155], off
	s_waitcnt vmcnt(8)
	s_waitcnt lgkmcnt(0)
	s_barrier
	s_waitcnt lgkmcnt(0)
	v_mfma_f32_16x16x32_bf16 v[64:67], v[116:119], v[190:193], v[64:67]
	v_mfma_f32_16x16x32_bf16 v[68:71], v[124:127], v[190:193], v[68:71]
	v_mfma_f32_16x16x32_bf16 v[72:75], v[116:119], v[198:201], v[72:75]
	v_mfma_f32_16x16x32_bf16 v[76:79], v[124:127], v[198:201], v[76:79]
	v_mfma_f32_16x16x32_bf16 v[80:83], v[116:119], v[218:221], v[80:83]
	v_mfma_f32_16x16x32_bf16 v[84:87], v[124:127], v[218:221], v[84:87]
	v_mfma_f32_16x16x32_bf16 v[88:91], v[116:119], v[226:229], v[88:91]
	v_mfma_f32_16x16x32_bf16 v[92:95], v[124:127], v[226:229], v[92:95]
	v_mfma_f32_16x16x32_bf16 v[64:67], v[120:123], v[194:197], v[64:67]
	v_mfma_f32_16x16x32_bf16 v[68:71], v[134:137], v[194:197], v[68:71]
	v_mfma_f32_16x16x32_bf16 v[72:75], v[120:123], v[202:205], v[72:75]
	v_mfma_f32_16x16x32_bf16 v[76:79], v[134:137], v[202:205], v[76:79]
	v_mfma_f32_16x16x32_bf16 v[80:83], v[120:123], v[222:225], v[80:83]
	v_mfma_f32_16x16x32_bf16 v[84:87], v[134:137], v[222:225], v[84:87]
	v_mfma_f32_16x16x32_bf16 v[88:91], v[120:123], v[230:233], v[88:91]
	v_mfma_f32_16x16x32_bf16 v[92:95], v[134:137], v[230:233], v[92:95]
	v_mfma_f32_16x16x32_bf16 v[96:99], v[140:143], v[190:193], v[96:99]
	v_mfma_f32_16x16x32_bf16 v[100:103], v[182:185], v[190:193], v[100:103]
	v_mfma_f32_16x16x32_bf16 v[104:107], v[140:143], v[198:201], v[104:107]
	v_mfma_f32_16x16x32_bf16 v[40:43], v[182:185], v[198:201], v[40:43]
	v_mfma_f32_16x16x32_bf16 v[44:47], v[140:143], v[218:221], v[44:47]
	v_mfma_f32_16x16x32_bf16 v[48:51], v[182:185], v[218:221], v[48:51]
	v_mfma_f32_16x16x32_bf16 v[52:55], v[140:143], v[226:229], v[52:55]
	v_mfma_f32_16x16x32_bf16 v[56:59], v[182:185], v[226:229], v[56:59]
	v_mfma_f32_16x16x32_bf16 v[96:99], v[144:147], v[194:197], v[96:99]
	v_mfma_f32_16x16x32_bf16 v[100:103], v[186:189], v[194:197], v[100:103]
	v_mfma_f32_16x16x32_bf16 v[104:107], v[144:147], v[202:205], v[104:107]
	v_mfma_f32_16x16x32_bf16 v[40:43], v[186:189], v[202:205], v[40:43]
	v_mfma_f32_16x16x32_bf16 v[44:47], v[144:147], v[222:225], v[44:47]
	v_mfma_f32_16x16x32_bf16 v[48:51], v[186:189], v[222:225], v[48:51]
	v_mfma_f32_16x16x32_bf16 v[52:55], v[144:147], v[230:233], v[52:55]
	v_mfma_f32_16x16x32_bf16 v[56:59], v[186:189], v[230:233], v[56:59]
	s_barrier
	s_mov_b64 s[56:57], 0x280
	s_mov_b32 m0, s55
	v_lshl_add_u64 v[0:1], v[0:1], 0, s[56:57]
	s_add_u32 s26, s26, 0x18280
	ds_read_b128 v[190:193], v139 offset:49152
	ds_read_b128 v[194:197], v139 offset:50176
	ds_read_b128 v[198:201], v139 offset:51200
	ds_read_b128 v[202:205], v139 offset:52224
	ds_read_b128 v[218:221], v139 offset:53248
	ds_read_b128 v[222:225], v139 offset:54272
	ds_read_b128 v[226:229], v139 offset:55296
	ds_read_b128 v[230:233], v139 offset:56320
	global_load_lds_dwordx4 v[0:1], off
	v_lshl_add_u64 v[0:1], v[2:3], 0, s[56:57]
	s_mov_b32 m0, s51
	s_addc_u32 s27, s27, 0
	global_load_lds_dwordx4 v[0:1], off
	v_lshl_add_u64 v[0:1], s[26:27], 0, v[148:149]
	s_mov_b32 m0, s52
	s_nop 0
	global_load_lds_dwordx4 v[0:1], off
	v_lshl_add_u64 v[0:1], s[26:27], 0, v[128:129]
	s_mov_b32 m0, s54
	s_nop 0
	global_load_lds_dwordx4 v[0:1], off
	v_lshl_add_u64 v[0:1], v[4:5], 0, s[56:57]
	s_mov_b32 m0, s42
	s_nop 0
	global_load_lds_dwordx4 v[0:1], off
	v_lshl_add_u64 v[0:1], v[6:7], 0, s[56:57]
	s_mov_b32 m0, s43
	s_nop 0
	global_load_lds_dwordx4 v[0:1], off
	s_waitcnt vmcnt(8)
	s_waitcnt lgkmcnt(0)
	s_barrier
	s_waitcnt lgkmcnt(0)
	v_mfma_f32_16x16x32_bf16 v[0:3], v[116:119], v[190:193], v[158:161]
	v_mfma_f32_16x16x32_bf16 v[4:7], v[124:127], v[190:193], v[162:165]
	v_mfma_f32_16x16x32_bf16 v[12:15], v[116:119], v[226:229], v[12:15]
	v_mfma_f32_16x16x32_bf16 v[16:19], v[124:127], v[226:229], v[16:19]
	v_mfma_f32_16x16x32_bf16 v[0:3], v[120:123], v[194:197], v[0:3]
	v_mfma_f32_16x16x32_bf16 v[4:7], v[134:137], v[194:197], v[4:7]
	v_mfma_f32_16x16x32_bf16 v[158:161], v[116:119], v[198:201], v[166:169]
	v_mfma_f32_16x16x32_bf16 v[162:165], v[124:127], v[198:201], v[170:173]
	v_mfma_f32_16x16x32_bf16 v[166:169], v[116:119], v[218:221], v[174:177]
	v_mfma_f32_16x16x32_bf16 v[170:173], v[124:127], v[218:221], v[178:181]
	v_mfma_f32_16x16x32_bf16 v[12:15], v[120:123], v[230:233], v[12:15]
	v_mfma_f32_16x16x32_bf16 v[16:19], v[134:137], v[230:233], v[16:19]
	v_mfma_f32_16x16x32_bf16 v[158:161], v[120:123], v[202:205], v[158:161]
	v_mfma_f32_16x16x32_bf16 v[162:165], v[134:137], v[202:205], v[162:165]
	v_mfma_f32_16x16x32_bf16 v[166:169], v[120:123], v[222:225], v[166:169]
	v_mfma_f32_16x16x32_bf16 v[170:173], v[134:137], v[222:225], v[170:173]
	v_mfma_f32_16x16x32_bf16 v[20:23], v[140:143], v[190:193], v[20:23]
	v_mfma_f32_16x16x32_bf16 v[32:35], v[182:185], v[190:193], v[32:35]
	v_mfma_f32_16x16x32_bf16 v[36:39], v[140:143], v[198:201], v[36:39]
	v_mfma_f32_16x16x32_bf16 v[60:63], v[182:185], v[198:201], v[60:63]
	v_mfma_f32_16x16x32_bf16 v[108:111], v[140:143], v[218:221], v[108:111]
	v_mfma_f32_16x16x32_bf16 v[112:115], v[182:185], v[218:221], v[112:115]
	v_mfma_f32_16x16x32_bf16 v[24:27], v[140:143], v[226:229], v[24:27]
	v_mfma_f32_16x16x32_bf16 v[28:31], v[182:185], v[226:229], v[28:31]
	v_mfma_f32_16x16x32_bf16 v[20:23], v[144:147], v[194:197], v[20:23]
	v_mfma_f32_16x16x32_bf16 v[32:35], v[186:189], v[194:197], v[32:35]
	v_mfma_f32_16x16x32_bf16 v[36:39], v[144:147], v[202:205], v[36:39]
	v_mfma_f32_16x16x32_bf16 v[60:63], v[186:189], v[202:205], v[60:63]
	v_mfma_f32_16x16x32_bf16 v[108:111], v[144:147], v[222:225], v[108:111]
	v_mfma_f32_16x16x32_bf16 v[112:115], v[186:189], v[222:225], v[112:115]
	v_mfma_f32_16x16x32_bf16 v[24:27], v[144:147], v[230:233], v[24:27]
	v_mfma_f32_16x16x32_bf16 v[28:31], v[186:189], v[230:233], v[28:31]
	s_barrier
	ds_read_b128 v[116:119], v8
	ds_read_b128 v[120:123], v8 offset:1024
	ds_read_b128 v[124:127], v8 offset:2048
	ds_read_b128 v[134:137], v8 offset:3072
	ds_read_b128 v[140:143], v9
	ds_read_b128 v[144:147], v9 offset:1024
	ds_read_b128 v[174:177], v9 offset:2048
	ds_read_b128 v[178:181], v9 offset:3072
	s_add_u32 s24, s24, 0x20280
	s_addc_u32 s25, s25, 0
	s_mov_b32 m0, s53
	v_lshl_add_u64 v[8:9], s[24:25], 0, v[132:133]
	ds_read_b128 v[182:185], v139
	ds_read_b128 v[186:189], v139 offset:1024
	ds_read_b128 v[190:193], v139 offset:2048
	ds_read_b128 v[194:197], v139 offset:3072
	ds_read_b128 v[198:201], v139 offset:4096
	ds_read_b128 v[202:205], v139 offset:5120
	ds_read_b128 v[218:221], v139 offset:6144
	ds_read_b128 v[222:225], v139 offset:7168
	global_load_lds_dwordx4 v[8:9], off
	v_lshl_add_u64 v[8:9], s[24:25], 0, v[130:131]
	s_mov_b32 m0, s19
	s_nop 0
	global_load_lds_dwordx4 v[8:9], off
	s_waitcnt vmcnt(8)
	s_waitcnt lgkmcnt(0)
	s_barrier
	s_waitcnt lgkmcnt(0)
	v_mfma_f32_16x16x32_bf16 v[64:67], v[116:119], v[182:185], v[64:67]
	v_mfma_f32_16x16x32_bf16 v[68:71], v[124:127], v[182:185], v[68:71]
	v_mfma_f32_16x16x32_bf16 v[72:75], v[116:119], v[190:193], v[72:75]
	v_mfma_f32_16x16x32_bf16 v[76:79], v[124:127], v[190:193], v[76:79]
	v_mfma_f32_16x16x32_bf16 v[80:83], v[116:119], v[198:201], v[80:83]
	v_mfma_f32_16x16x32_bf16 v[84:87], v[124:127], v[198:201], v[84:87]
	v_mfma_f32_16x16x32_bf16 v[88:91], v[116:119], v[218:221], v[88:91]
	v_mfma_f32_16x16x32_bf16 v[92:95], v[124:127], v[218:221], v[92:95]
	v_mfma_f32_16x16x32_bf16 v[64:67], v[120:123], v[186:189], v[64:67]
	v_mfma_f32_16x16x32_bf16 v[68:71], v[134:137], v[186:189], v[68:71]
	v_mfma_f32_16x16x32_bf16 v[72:75], v[120:123], v[194:197], v[72:75]
	v_mfma_f32_16x16x32_bf16 v[76:79], v[134:137], v[194:197], v[76:79]
	v_mfma_f32_16x16x32_bf16 v[80:83], v[120:123], v[202:205], v[80:83]
	v_mfma_f32_16x16x32_bf16 v[84:87], v[134:137], v[202:205], v[84:87]
	v_mfma_f32_16x16x32_bf16 v[88:91], v[120:123], v[222:225], v[88:91]
	v_mfma_f32_16x16x32_bf16 v[92:95], v[134:137], v[222:225], v[92:95]
	v_mfma_f32_16x16x32_bf16 v[96:99], v[140:143], v[182:185], v[96:99]
	v_mfma_f32_16x16x32_bf16 v[226:229], v[144:147], v[186:189], v[96:99]
	v_mfma_f32_16x16x32_bf16 v[96:99], v[174:177], v[182:185], v[100:103]
	v_mfma_f32_16x16x32_bf16 v[182:185], v[178:181], v[186:189], v[96:99]
	v_mfma_f32_16x16x32_bf16 v[96:99], v[140:143], v[190:193], v[104:107]
	v_mfma_f32_16x16x32_bf16 v[40:43], v[174:177], v[190:193], v[40:43]
	v_mfma_f32_16x16x32_bf16 v[44:47], v[140:143], v[198:201], v[44:47]
	v_mfma_f32_16x16x32_bf16 v[48:51], v[174:177], v[198:201], v[48:51]
	v_mfma_f32_16x16x32_bf16 v[52:55], v[140:143], v[218:221], v[52:55]
	v_mfma_f32_16x16x32_bf16 v[56:59], v[174:177], v[218:221], v[56:59]
	v_mfma_f32_16x16x32_bf16 v[104:107], v[144:147], v[194:197], v[96:99]
	v_mfma_f32_16x16x32_bf16 v[40:43], v[178:181], v[194:197], v[40:43]
	v_mfma_f32_16x16x32_bf16 v[44:47], v[144:147], v[202:205], v[44:47]
	v_mfma_f32_16x16x32_bf16 v[48:51], v[178:181], v[202:205], v[48:51]
	v_mfma_f32_16x16x32_bf16 v[52:55], v[144:147], v[222:225], v[52:55]
	v_mfma_f32_16x16x32_bf16 v[56:59], v[178:181], v[222:225], v[56:59]
	s_barrier
	s_mov_b32 m0, s50
	v_lshl_add_u64 v[154:155], s[20:21], 0, v[148:149]
	s_add_u32 s24, s20, 0x18000
	ds_read_b128 v[96:99], v139 offset:16384
	ds_read_b128 v[100:103], v139 offset:17408
	ds_read_b128 v[186:189], v139 offset:18432
	ds_read_b128 v[190:193], v139 offset:19456
	ds_read_b128 v[194:197], v139 offset:20480
	ds_read_b128 v[198:201], v139 offset:21504
	ds_read_b128 v[202:205], v139 offset:22528
	ds_read_b128 v[218:221], v139 offset:23552
	global_load_lds_dwordx4 v[154:155], off
	v_lshl_add_u64 v[156:157], s[20:21], 0, v[128:129]
	s_mov_b32 m0, s47
	s_addc_u32 s25, s21, 0
	global_load_lds_dwordx4 v[156:157], off
	v_lshl_add_u64 v[8:9], s[24:25], 0, v[148:149]
	s_mov_b32 m0, s48
	v_lshl_add_u64 v[212:213], s[0:1], 0, v[132:133]
	global_load_lds_dwordx4 v[8:9], off
	v_lshl_add_u64 v[8:9], s[24:25], 0, v[128:129]
	s_mov_b32 m0, s49
	v_lshl_add_u64 v[214:215], s[0:1], 0, v[130:131]
	global_load_lds_dwordx4 v[8:9], off
	s_mov_b32 m0, s36
	s_nop 0
	global_load_lds_dwordx4 v[212:213], off
	s_mov_b32 m0, s37
	s_nop 0
	global_load_lds_dwordx4 v[214:215], off
	s_waitcnt vmcnt(8)
	s_waitcnt lgkmcnt(0)
	s_barrier
	s_waitcnt lgkmcnt(0)
	v_mfma_f32_16x16x32_bf16 v[0:3], v[116:119], v[96:99], v[0:3]
	v_mfma_f32_16x16x32_bf16 v[4:7], v[124:127], v[96:99], v[4:7]
	v_mfma_f32_16x16x32_bf16 v[12:15], v[116:119], v[202:205], v[12:15]
	v_mfma_f32_16x16x32_bf16 v[0:3], v[120:123], v[100:103], v[0:3]
	v_mfma_f32_16x16x32_bf16 v[4:7], v[134:137], v[100:103], v[4:7]
	v_mfma_f32_16x16x32_bf16 v[158:161], v[116:119], v[186:189], v[158:161]
	v_mfma_f32_16x16x32_bf16 v[162:165], v[124:127], v[186:189], v[162:165]
	v_mfma_f32_16x16x32_bf16 v[166:169], v[116:119], v[194:197], v[166:169]
	v_mfma_f32_16x16x32_bf16 v[170:173], v[124:127], v[194:197], v[170:173]
	v_mfma_f32_16x16x32_bf16 v[12:15], v[120:123], v[218:221], v[12:15]
	v_mfma_f32_16x16x32_bf16 v[16:19], v[124:127], v[202:205], v[16:19]
	v_mfma_f32_16x16x32_bf16 v[158:161], v[120:123], v[190:193], v[158:161]
	v_mfma_f32_16x16x32_bf16 v[162:165], v[134:137], v[190:193], v[162:165]
	v_mfma_f32_16x16x32_bf16 v[166:169], v[120:123], v[198:201], v[166:169]
	v_mfma_f32_16x16x32_bf16 v[170:173], v[134:137], v[198:201], v[170:173]
	v_mfma_f32_16x16x32_bf16 v[134:137], v[134:137], v[218:221], v[16:19]
	v_mfma_f32_16x16x32_bf16 v[16:19], v[140:143], v[96:99], v[20:23]
	v_mfma_f32_16x16x32_bf16 v[222:225], v[144:147], v[100:103], v[16:19]
	v_mfma_f32_16x16x32_bf16 v[16:19], v[174:177], v[96:99], v[32:35]
	v_mfma_f32_16x16x32_bf16 v[230:233], v[178:181], v[100:103], v[16:19]
	v_mfma_f32_16x16x32_bf16 v[16:19], v[140:143], v[186:189], v[36:39]
	v_mfma_f32_16x16x32_bf16 v[234:237], v[144:147], v[190:193], v[16:19]
	v_mfma_f32_16x16x32_bf16 v[16:19], v[174:177], v[186:189], v[60:63]
	v_mfma_f32_16x16x32_bf16 v[186:189], v[178:181], v[190:193], v[16:19]
	v_mfma_f32_16x16x32_bf16 v[16:19], v[140:143], v[194:197], v[108:111]
	v_mfma_f32_16x16x32_bf16 v[190:193], v[144:147], v[198:201], v[16:19]
	v_mfma_f32_16x16x32_bf16 v[16:19], v[174:177], v[194:197], v[112:115]
	v_mfma_f32_16x16x32_bf16 v[194:197], v[178:181], v[198:201], v[16:19]
	v_mfma_f32_16x16x32_bf16 v[16:19], v[140:143], v[202:205], v[24:27]
	v_mfma_f32_16x16x32_bf16 v[140:143], v[144:147], v[218:221], v[16:19]
	v_mfma_f32_16x16x32_bf16 v[16:19], v[174:177], v[202:205], v[28:31]
	v_mfma_f32_16x16x32_bf16 v[144:147], v[178:181], v[218:221], v[16:19]
	s_barrier
	ds_read_b128 v[24:27], v10
	ds_read_b128 v[28:31], v10 offset:1024
	ds_read_b128 v[60:63], v10 offset:2048
	ds_read_b128 v[174:177], v10 offset:3072
	ds_read_b128 v[178:181], v11
	ds_read_b128 v[198:201], v11 offset:1024
	ds_read_b128 v[202:205], v11 offset:2048
	ds_read_b128 v[218:221], v11 offset:3072
	s_add_u32 s0, s0, 0x20000
	s_addc_u32 s1, s1, 0
	s_mov_b32 m0, s38
	v_lshl_add_u64 v[96:97], s[0:1], 0, v[132:133]
	ds_read_b128 v[8:11], v139 offset:32768
	ds_read_b128 v[16:19], v139 offset:33792
	ds_read_b128 v[20:23], v139 offset:34816
	ds_read_b128 v[32:35], v139 offset:35840
	ds_read_b128 v[36:39], v139 offset:36864
	ds_read_b128 v[238:241], v139 offset:37888
	ds_read_b128 v[242:245], v139 offset:38912
	ds_read_b128 v[246:249], v139 offset:39936
	global_load_lds_dwordx4 v[96:97], off
	v_lshl_add_u64 v[96:97], s[0:1], 0, v[130:131]
	s_mov_b32 m0, s39
	s_nop 0
	global_load_lds_dwordx4 v[96:97], off
	s_waitcnt vmcnt(8)
	s_waitcnt lgkmcnt(0)
	s_barrier
	s_waitcnt lgkmcnt(0)
	v_mfma_f32_16x16x32_bf16 v[64:67], v[24:27], v[8:11], v[64:67]
	v_mfma_f32_16x16x32_bf16 v[112:115], v[28:31], v[16:19], v[64:67]
	v_mfma_f32_16x16x32_bf16 v[64:67], v[60:63], v[8:11], v[68:71]
	v_mfma_f32_16x16x32_bf16 v[116:119], v[174:177], v[16:19], v[64:67]
	v_mfma_f32_16x16x32_bf16 v[64:67], v[24:27], v[20:23], v[72:75]
	v_mfma_f32_16x16x32_bf16 v[96:99], v[28:31], v[32:35], v[64:67]
	v_mfma_f32_16x16x32_bf16 v[64:67], v[60:63], v[20:23], v[76:79]
	v_mfma_f32_16x16x32_bf16 v[100:103], v[174:177], v[32:35], v[64:67]
	v_mfma_f32_16x16x32_bf16 v[64:67], v[24:27], v[36:39], v[80:83]
	v_mfma_f32_16x16x32_bf16 v[80:83], v[28:31], v[238:241], v[64:67]
	v_mfma_f32_16x16x32_bf16 v[64:67], v[60:63], v[36:39], v[84:87]
	v_mfma_f32_16x16x32_bf16 v[84:87], v[174:177], v[238:241], v[64:67]
	v_mfma_f32_16x16x32_bf16 v[64:67], v[24:27], v[242:245], v[88:91]
	v_mfma_f32_16x16x32_bf16 v[68:71], v[60:63], v[242:245], v[92:95]
	v_mfma_f32_16x16x32_bf16 v[64:67], v[28:31], v[246:249], v[64:67]
	v_mfma_f32_16x16x32_bf16 v[68:71], v[174:177], v[246:249], v[68:71]
	v_mfma_f32_16x16x32_bf16 v[72:75], v[178:181], v[8:11], v[226:229]
	v_mfma_f32_16x16x32_bf16 v[8:11], v[202:205], v[8:11], v[182:185]
	v_mfma_f32_16x16x32_bf16 v[124:127], v[218:221], v[16:19], v[8:11]
	v_mfma_f32_16x16x32_bf16 v[8:11], v[178:181], v[20:23], v[104:107]
	v_mfma_f32_16x16x32_bf16 v[104:107], v[198:201], v[32:35], v[8:11]
	v_mfma_f32_16x16x32_bf16 v[8:11], v[202:205], v[20:23], v[40:43]
	v_mfma_f32_16x16x32_bf16 v[108:111], v[218:221], v[32:35], v[8:11]
	v_mfma_f32_16x16x32_bf16 v[8:11], v[178:181], v[36:39], v[44:47]
	v_mfma_f32_16x16x32_bf16 v[88:91], v[198:201], v[238:241], v[8:11]
	v_mfma_f32_16x16x32_bf16 v[8:11], v[202:205], v[36:39], v[48:51]
	v_mfma_f32_16x16x32_bf16 v[92:95], v[218:221], v[238:241], v[8:11]
	v_mfma_f32_16x16x32_bf16 v[8:11], v[178:181], v[242:245], v[52:55]
	v_mfma_f32_16x16x32_bf16 v[120:123], v[198:201], v[16:19], v[72:75]
	v_mfma_f32_16x16x32_bf16 v[72:75], v[198:201], v[246:249], v[8:11]
	v_mfma_f32_16x16x32_bf16 v[8:11], v[202:205], v[242:245], v[56:59]
	v_mfma_f32_16x16x32_bf16 v[76:79], v[218:221], v[246:249], v[8:11]
	s_barrier
	s_mov_b32 m0, s55
	v_lshl_add_u64 v[16:17], v[154:155], 0, s[28:29]
	s_add_u32 s0, s20, 0x18080
	s_nop 1
	ds_read_b128 v[8:11], v139 offset:49152
	ds_read_b128 v[40:43], v139 offset:50176
	ds_read_b128 v[44:47], v139 offset:51200
	ds_read_b128 v[182:185], v139 offset:52224
	ds_read_b128 v[226:229], v139 offset:53248
	ds_read_b128 v[238:241], v139 offset:54272
	ds_read_b128 v[242:245], v139 offset:55296
	ds_read_b128 v[246:249], v139 offset:56320
	global_load_lds_dwordx4 v[16:17], off
	v_lshl_add_u64 v[16:17], v[156:157], 0, s[28:29]
	s_mov_b32 m0, s51
	s_addc_u32 s1, s21, 0
	global_load_lds_dwordx4 v[16:17], off
	v_lshl_add_u64 v[16:17], s[0:1], 0, v[148:149]
	s_mov_b32 m0, s52
	s_nop 0
	global_load_lds_dwordx4 v[16:17], off
	v_lshl_add_u64 v[16:17], s[0:1], 0, v[128:129]
	s_mov_b32 m0, s54
	s_nop 0
	global_load_lds_dwordx4 v[16:17], off
	v_lshl_add_u64 v[16:17], v[212:213], 0, s[28:29]
	s_mov_b32 m0, s42
	s_nop 0
	global_load_lds_dwordx4 v[16:17], off
	v_lshl_add_u64 v[16:17], v[214:215], 0, s[28:29]
	s_mov_b32 m0, s43
	s_nop 0
	global_load_lds_dwordx4 v[16:17], off
	s_waitcnt vmcnt(8)
	s_waitcnt lgkmcnt(0)
	s_barrier
	s_waitcnt lgkmcnt(0)
	v_mfma_f32_16x16x32_bf16 v[0:3], v[24:27], v[8:11], v[0:3]
	v_mfma_f32_16x16x32_bf16 v[48:51], v[28:31], v[40:43], v[0:3]
	v_mfma_f32_16x16x32_bf16 v[0:3], v[60:63], v[8:11], v[4:7]
	v_mfma_f32_16x16x32_bf16 v[52:55], v[174:177], v[40:43], v[0:3]
	v_mfma_f32_16x16x32_bf16 v[0:3], v[24:27], v[44:47], v[158:161]
	v_mfma_f32_16x16x32_bf16 v[32:35], v[28:31], v[182:185], v[0:3]
	v_mfma_f32_16x16x32_bf16 v[0:3], v[60:63], v[44:47], v[162:165]
	v_mfma_f32_16x16x32_bf16 v[36:39], v[174:177], v[182:185], v[0:3]
	v_mfma_f32_16x16x32_bf16 v[0:3], v[24:27], v[226:229], v[166:169]
	v_mfma_f32_16x16x32_bf16 v[16:19], v[28:31], v[238:241], v[0:3]
	v_mfma_f32_16x16x32_bf16 v[0:3], v[60:63], v[226:229], v[170:173]
	v_mfma_f32_16x16x32_bf16 v[20:23], v[174:177], v[238:241], v[0:3]
	v_mfma_f32_16x16x32_bf16 v[0:3], v[24:27], v[242:245], v[12:15]
	v_mfma_f32_16x16x32_bf16 v[4:7], v[60:63], v[242:245], v[134:137]
	v_mfma_f32_16x16x32_bf16 v[0:3], v[28:31], v[246:249], v[0:3]
	v_mfma_f32_16x16x32_bf16 v[4:7], v[174:177], v[246:249], v[4:7]
	v_mfma_f32_16x16x32_bf16 v[12:15], v[178:181], v[8:11], v[222:225]
	v_mfma_f32_16x16x32_bf16 v[8:11], v[202:205], v[8:11], v[230:233]
	v_mfma_f32_16x16x32_bf16 v[60:63], v[218:221], v[40:43], v[8:11]
	v_mfma_f32_16x16x32_bf16 v[8:11], v[178:181], v[44:47], v[234:237]
	v_mfma_f32_16x16x32_bf16 v[56:59], v[198:201], v[40:43], v[12:15]
	v_mfma_f32_16x16x32_bf16 v[40:43], v[198:201], v[182:185], v[8:11]
	v_mfma_f32_16x16x32_bf16 v[8:11], v[202:205], v[44:47], v[186:189]
	v_mfma_f32_16x16x32_bf16 v[44:47], v[218:221], v[182:185], v[8:11]
	v_mfma_f32_16x16x32_bf16 v[8:11], v[178:181], v[226:229], v[190:193]
	v_mfma_f32_16x16x32_bf16 v[24:27], v[198:201], v[238:241], v[8:11]
	v_mfma_f32_16x16x32_bf16 v[8:11], v[202:205], v[226:229], v[194:197]
	v_mfma_f32_16x16x32_bf16 v[28:31], v[218:221], v[238:241], v[8:11]
	v_mfma_f32_16x16x32_bf16 v[8:11], v[178:181], v[242:245], v[140:143]
	v_mfma_f32_16x16x32_bf16 v[12:15], v[202:205], v[242:245], v[144:147]
	v_mfma_f32_16x16x32_bf16 v[8:11], v[198:201], v[246:249], v[8:11]
	v_mfma_f32_16x16x32_bf16 v[12:15], v[218:221], v[246:249], v[12:15]
	s_barrier
	s_andn2_b64 vcc, exec, s[14:15]
	s_cbranch_vccnz .LBB0_855
	s_barrier

.LBB0_871:
	s_ashr_i32 s19, s18, 31
	s_lshl_b64 s[20:21], s[18:19], 17
	s_add_u32 s20, s33, s20
	s_addc_u32 s21, s36, s21
	s_and_b64 s[22:23], s[0:1], exec
	s_cselect_b32 s35, s21, s25
	s_cselect_b32 s34, s20, s24
	s_ashr_i32 s17, s16, 31
	s_lshl_b64 s[22:23], s[16:17], 17
	s_add_u32 s22, s37, s22
	s_addc_u32 s23, s38, s23
	s_and_b64 s[30:31], s[0:1], exec
	s_cselect_b32 s31, s23, s27
	s_cselect_b32 s30, s22, s26
	s_add_i32 s52, 0, 0x10000
	s_add_i32 s53, 0, 0x14000
	v_add_u32_e32 v150, s52, v138
	v_add_u32_e32 v151, s53, v138
	ds_read_b128 v[0:3], v150
	ds_read_b128 v[4:7], v150 offset:1024
	ds_read_b128 v[8:11], v150 offset:2048
	ds_read_b128 v[12:15], v150 offset:3072
	ds_read_b128 v[16:19], v151
	ds_read_b128 v[20:23], v151 offset:1024
	ds_read_b128 v[24:27], v151 offset:2048
	ds_read_b128 v[28:31], v151 offset:3072
	s_add_u32 s50, s24, 0x10080
	s_addc_u32 s51, s25, 0
	s_add_i32 s54, s40, 0xc000
	v_lshl_add_u64 v[64:65], s[50:51], 0, v[132:133]
	s_mov_b32 m0, s54
	s_add_i32 s17, s40, 0xe000
	ds_read_b128 v[32:35], v139
	ds_read_b128 v[36:39], v139 offset:1024
	ds_read_b128 v[40:43], v139 offset:2048
	ds_read_b128 v[44:47], v139 offset:3072
	ds_read_b128 v[48:51], v139 offset:4096
	ds_read_b128 v[52:55], v139 offset:5120
	ds_read_b128 v[56:59], v139 offset:6144
	ds_read_b128 v[60:63], v139 offset:7168
	global_load_lds_dwordx4 v[64:65], off
	v_lshl_add_u64 v[64:65], s[50:51], 0, v[130:131]
	s_mov_b32 m0, s17
	s_nop 0
	global_load_lds_dwordx4 v[64:65], off
	s_waitcnt vmcnt(8)
	s_waitcnt lgkmcnt(0)
	s_barrier
	s_waitcnt lgkmcnt(0)
	v_mfma_f32_16x16x32_bf16 v[64:67], v[0:3], v[32:35], 0
	v_mfma_f32_16x16x32_bf16 v[68:71], v[8:11], v[32:35], 0
	v_mfma_f32_16x16x32_bf16 v[72:75], v[0:3], v[40:43], 0
	v_mfma_f32_16x16x32_bf16 v[76:79], v[8:11], v[40:43], 0
	v_mfma_f32_16x16x32_bf16 v[80:83], v[0:3], v[48:51], 0
	v_mfma_f32_16x16x32_bf16 v[84:87], v[8:11], v[48:51], 0
	v_mfma_f32_16x16x32_bf16 v[88:91], v[0:3], v[56:59], 0
	v_mfma_f32_16x16x32_bf16 v[92:95], v[8:11], v[56:59], 0
	v_mfma_f32_16x16x32_bf16 v[64:67], v[4:7], v[36:39], v[64:67]
	v_mfma_f32_16x16x32_bf16 v[68:71], v[12:15], v[36:39], v[68:71]
	v_mfma_f32_16x16x32_bf16 v[72:75], v[4:7], v[44:47], v[72:75]
	v_mfma_f32_16x16x32_bf16 v[76:79], v[12:15], v[44:47], v[76:79]
	v_mfma_f32_16x16x32_bf16 v[80:83], v[4:7], v[52:55], v[80:83]
	v_mfma_f32_16x16x32_bf16 v[84:87], v[12:15], v[52:55], v[84:87]
	v_mfma_f32_16x16x32_bf16 v[88:91], v[4:7], v[60:63], v[88:91]
	v_mfma_f32_16x16x32_bf16 v[92:95], v[12:15], v[60:63], v[92:95]
	v_mfma_f32_16x16x32_bf16 v[96:99], v[16:19], v[32:35], 0
	v_mfma_f32_16x16x32_bf16 v[32:35], v[24:27], v[32:35], 0
	v_mfma_f32_16x16x32_bf16 v[96:99], v[20:23], v[36:39], v[96:99]
	v_mfma_f32_16x16x32_bf16 v[32:35], v[28:31], v[36:39], v[32:35]
	v_mfma_f32_16x16x32_bf16 v[36:39], v[16:19], v[40:43], 0
	v_mfma_f32_16x16x32_bf16 v[40:43], v[24:27], v[40:43], 0
	v_mfma_f32_16x16x32_bf16 v[36:39], v[20:23], v[44:47], v[36:39]
	v_mfma_f32_16x16x32_bf16 v[40:43], v[28:31], v[44:47], v[40:43]
	v_mfma_f32_16x16x32_bf16 v[44:47], v[16:19], v[48:51], 0
	v_mfma_f32_16x16x32_bf16 v[48:51], v[24:27], v[48:51], 0
	v_mfma_f32_16x16x32_bf16 v[44:47], v[20:23], v[52:55], v[44:47]
	v_mfma_f32_16x16x32_bf16 v[48:51], v[28:31], v[52:55], v[48:51]
	v_mfma_f32_16x16x32_bf16 v[52:55], v[16:19], v[56:59], 0
	v_mfma_f32_16x16x32_bf16 v[56:59], v[24:27], v[56:59], 0
	v_mfma_f32_16x16x32_bf16 v[52:55], v[20:23], v[60:63], v[52:55]
	v_mfma_f32_16x16x32_bf16 v[56:59], v[28:31], v[60:63], v[56:59]
	s_barrier
	s_add_i32 s52, s52, s39
	v_lshl_add_u64 v[154:155], s[26:27], 0, v[148:149]
	s_mov_b64 s[60:61], 0x100
	s_add_i32 s19, s52, 0x2000
	v_lshl_add_u64 v[134:135], v[154:155], 0, s[60:61]
	s_mov_b32 m0, s52
	v_lshl_add_u64 v[156:157], s[26:27], 0, v[128:129]
	s_add_u32 s56, s26, 0x10100
	ds_read_b128 v[60:63], v139 offset:16384
	ds_read_b128 v[100:103], v139 offset:17408
	ds_read_b128 v[104:107], v139 offset:18432
	ds_read_b128 v[108:111], v139 offset:19456
	ds_read_b128 v[112:115], v139 offset:20480
	ds_read_b128 v[116:119], v139 offset:21504
	ds_read_b128 v[120:123], v139 offset:22528
	ds_read_b128 v[124:127], v139 offset:23552
	global_load_lds_dwordx4 v[134:135], off
	v_lshl_add_u64 v[134:135], v[156:157], 0, s[60:61]
	s_mov_b32 m0, s19
	s_addc_u32 s57, s27, 0
	s_add_i32 s50, s53, s39
	global_load_lds_dwordx4 v[134:135], off
	v_lshl_add_u64 v[134:135], s[56:57], 0, v[148:149]
	s_mov_b32 m0, s50
	s_add_i32 s51, s50, 0x2000
	global_load_lds_dwordx4 v[134:135], off
	v_lshl_add_u64 v[134:135], s[56:57], 0, v[128:129]
	s_mov_b32 m0, s51
	v_lshl_add_u64 v[212:213], s[24:25], 0, v[132:133]
	global_load_lds_dwordx4 v[134:135], off
	v_lshl_add_u64 v[134:135], v[212:213], 0, s[60:61]
	s_mov_b32 m0, s40
	v_lshl_add_u64 v[214:215], s[24:25], 0, v[130:131]
	global_load_lds_dwordx4 v[134:135], off
	v_lshl_add_u64 v[134:135], v[214:215], 0, s[60:61]
	s_mov_b32 m0, s41
	s_nop 0
	global_load_lds_dwordx4 v[134:135], off
	s_waitcnt vmcnt(8)
	s_waitcnt lgkmcnt(0)
	s_barrier
	s_waitcnt lgkmcnt(0)
	v_mfma_f32_16x16x32_bf16 v[134:137], v[0:3], v[60:63], 0
	v_mfma_f32_16x16x32_bf16 v[144:147], v[0:3], v[104:107], 0
	v_mfma_f32_16x16x32_bf16 v[162:165], v[0:3], v[112:115], 0
	v_mfma_f32_16x16x32_bf16 v[0:3], v[0:3], v[120:123], 0
	v_mfma_f32_16x16x32_bf16 v[134:137], v[4:7], v[100:103], v[134:137]
	v_mfma_f32_16x16x32_bf16 v[144:147], v[4:7], v[108:111], v[144:147]
	v_mfma_f32_16x16x32_bf16 v[162:165], v[4:7], v[116:119], v[162:165]
	v_mfma_f32_16x16x32_bf16 v[0:3], v[4:7], v[124:127], v[0:3]
	v_mfma_f32_16x16x32_bf16 v[4:7], v[8:11], v[120:123], 0
	v_mfma_f32_16x16x32_bf16 v[140:143], v[8:11], v[60:63], 0
	v_mfma_f32_16x16x32_bf16 v[158:161], v[8:11], v[104:107], 0
	v_mfma_f32_16x16x32_bf16 v[166:169], v[8:11], v[112:115], 0
	v_mfma_f32_16x16x32_bf16 v[4:7], v[12:15], v[124:127], v[4:7]
	v_mfma_f32_16x16x32_bf16 v[140:143], v[12:15], v[100:103], v[140:143]
	v_mfma_f32_16x16x32_bf16 v[158:161], v[12:15], v[108:111], v[158:161]
	v_mfma_f32_16x16x32_bf16 v[166:169], v[12:15], v[116:119], v[166:169]
	v_mfma_f32_16x16x32_bf16 v[8:11], v[16:19], v[60:63], 0
	v_mfma_f32_16x16x32_bf16 v[12:15], v[24:27], v[60:63], 0
	v_mfma_f32_16x16x32_bf16 v[8:11], v[20:23], v[100:103], v[8:11]
	v_mfma_f32_16x16x32_bf16 v[12:15], v[28:31], v[100:103], v[12:15]
	v_mfma_f32_16x16x32_bf16 v[60:63], v[16:19], v[104:107], 0
	v_mfma_f32_16x16x32_bf16 v[100:103], v[24:27], v[104:107], 0
	v_mfma_f32_16x16x32_bf16 v[104:107], v[16:19], v[112:115], 0
	v_mfma_f32_16x16x32_bf16 v[16:19], v[16:19], v[120:123], 0
	v_mfma_f32_16x16x32_bf16 v[60:63], v[20:23], v[108:111], v[60:63]
	v_mfma_f32_16x16x32_bf16 v[100:103], v[28:31], v[108:111], v[100:103]
	v_mfma_f32_16x16x32_bf16 v[104:107], v[20:23], v[116:119], v[104:107]
	v_mfma_f32_16x16x32_bf16 v[108:111], v[24:27], v[112:115], 0
	v_mfma_f32_16x16x32_bf16 v[16:19], v[20:23], v[124:127], v[16:19]
	v_mfma_f32_16x16x32_bf16 v[20:23], v[24:27], v[120:123], 0
	v_mfma_f32_16x16x32_bf16 v[108:111], v[28:31], v[116:119], v[108:111]
	v_mfma_f32_16x16x32_bf16 v[20:23], v[28:31], v[124:127], v[20:23]
	s_barrier
	s_add_i32 s55, 0, 0x18000
	s_add_i32 s58, 0, 0x1c000
	v_add_u32_e32 v152, s55, v138
	v_add_u32_e32 v153, s58, v138
	ds_read_b128 v[24:27], v152
	ds_read_b128 v[28:31], v152 offset:1024
	ds_read_b128 v[112:115], v152 offset:2048
	ds_read_b128 v[116:119], v152 offset:3072
	ds_read_b128 v[120:123], v153
	ds_read_b128 v[124:127], v153 offset:1024
	ds_read_b128 v[170:173], v153 offset:2048
	ds_read_b128 v[174:177], v153 offset:3072
	s_add_u32 s56, s24, 0x10100
	s_addc_u32 s57, s25, 0
	s_mov_b32 m0, s42
	v_lshl_add_u64 v[222:223], s[56:57], 0, v[132:133]
	ds_read_b128 v[178:181], v139 offset:32768
	ds_read_b128 v[182:185], v139 offset:33792
	ds_read_b128 v[186:189], v139 offset:34816
	ds_read_b128 v[190:193], v139 offset:35840
	ds_read_b128 v[194:197], v139 offset:36864
	ds_read_b128 v[198:201], v139 offset:37888
	ds_read_b128 v[202:205], v139 offset:38912
	ds_read_b128 v[218:221], v139 offset:39936
	global_load_lds_dwordx4 v[222:223], off
	v_lshl_add_u64 v[222:223], s[56:57], 0, v[130:131]
	s_mov_b32 m0, s43
	s_nop 0
	global_load_lds_dwordx4 v[222:223], off
	s_waitcnt vmcnt(8)
	s_waitcnt lgkmcnt(0)
	s_barrier
	s_waitcnt lgkmcnt(0)
	v_mfma_f32_16x16x32_bf16 v[64:67], v[24:27], v[178:181], v[64:67]
	v_mfma_f32_16x16x32_bf16 v[68:71], v[112:115], v[178:181], v[68:71]
	v_mfma_f32_16x16x32_bf16 v[72:75], v[24:27], v[186:189], v[72:75]
	v_mfma_f32_16x16x32_bf16 v[76:79], v[112:115], v[186:189], v[76:79]
	v_mfma_f32_16x16x32_bf16 v[80:83], v[24:27], v[194:197], v[80:83]
	v_mfma_f32_16x16x32_bf16 v[84:87], v[112:115], v[194:197], v[84:87]
	v_mfma_f32_16x16x32_bf16 v[88:91], v[24:27], v[202:205], v[88:91]
	v_mfma_f32_16x16x32_bf16 v[92:95], v[112:115], v[202:205], v[92:95]
	v_mfma_f32_16x16x32_bf16 v[64:67], v[28:31], v[182:185], v[64:67]
	v_mfma_f32_16x16x32_bf16 v[68:71], v[116:119], v[182:185], v[68:71]
	v_mfma_f32_16x16x32_bf16 v[72:75], v[28:31], v[190:193], v[72:75]
	v_mfma_f32_16x16x32_bf16 v[76:79], v[116:119], v[190:193], v[76:79]
	v_mfma_f32_16x16x32_bf16 v[80:83], v[28:31], v[198:201], v[80:83]
	v_mfma_f32_16x16x32_bf16 v[84:87], v[116:119], v[198:201], v[84:87]
	v_mfma_f32_16x16x32_bf16 v[88:91], v[28:31], v[218:221], v[88:91]
	v_mfma_f32_16x16x32_bf16 v[92:95], v[116:119], v[218:221], v[92:95]
	v_mfma_f32_16x16x32_bf16 v[96:99], v[120:123], v[178:181], v[96:99]
	v_mfma_f32_16x16x32_bf16 v[32:35], v[170:173], v[178:181], v[32:35]
	v_mfma_f32_16x16x32_bf16 v[36:39], v[120:123], v[186:189], v[36:39]
	v_mfma_f32_16x16x32_bf16 v[40:43], v[170:173], v[186:189], v[40:43]
	v_mfma_f32_16x16x32_bf16 v[44:47], v[120:123], v[194:197], v[44:47]
	v_mfma_f32_16x16x32_bf16 v[48:51], v[170:173], v[194:197], v[48:51]
	v_mfma_f32_16x16x32_bf16 v[52:55], v[120:123], v[202:205], v[52:55]
	v_mfma_f32_16x16x32_bf16 v[56:59], v[170:173], v[202:205], v[56:59]
	v_mfma_f32_16x16x32_bf16 v[96:99], v[124:127], v[182:185], v[96:99]
	v_mfma_f32_16x16x32_bf16 v[32:35], v[174:177], v[182:185], v[32:35]
	v_mfma_f32_16x16x32_bf16 v[36:39], v[124:127], v[190:193], v[36:39]
	v_mfma_f32_16x16x32_bf16 v[40:43], v[174:177], v[190:193], v[40:43]
	v_mfma_f32_16x16x32_bf16 v[44:47], v[124:127], v[198:201], v[44:47]
	v_mfma_f32_16x16x32_bf16 v[48:51], v[174:177], v[198:201], v[48:51]
	v_mfma_f32_16x16x32_bf16 v[52:55], v[124:127], v[218:221], v[52:55]
	v_mfma_f32_16x16x32_bf16 v[56:59], v[174:177], v[218:221], v[56:59]
	s_barrier
	s_add_i32 s55, s55, s39
	s_mov_b64 s[60:61], 0x180
	s_add_i32 s53, s55, 0x2000
	v_lshl_add_u64 v[154:155], v[154:155], 0, s[60:61]
	s_mov_b32 m0, s55
	s_add_u32 s56, s26, 0x10180
	ds_read_b128 v[178:181], v139 offset:49152
	ds_read_b128 v[182:185], v139 offset:50176
	ds_read_b128 v[186:189], v139 offset:51200
	ds_read_b128 v[190:193], v139 offset:52224
	ds_read_b128 v[194:197], v139 offset:53248
	ds_read_b128 v[198:201], v139 offset:54272
	ds_read_b128 v[202:205], v139 offset:55296
	ds_read_b128 v[218:221], v139 offset:56320
	global_load_lds_dwordx4 v[154:155], off
	v_lshl_add_u64 v[154:155], v[156:157], 0, s[60:61]
	s_mov_b32 m0, s53
	s_addc_u32 s57, s27, 0
	s_add_i32 s26, s58, s39
	global_load_lds_dwordx4 v[154:155], off
	v_lshl_add_u64 v[154:155], s[56:57], 0, v[148:149]
	s_mov_b32 m0, s26
	s_add_i32 s27, s26, 0x2000
	global_load_lds_dwordx4 v[154:155], off
	v_lshl_add_u64 v[154:155], s[56:57], 0, v[128:129]
	s_mov_b32 m0, s27
	s_nop 0
	global_load_lds_dwordx4 v[154:155], off
	v_lshl_add_u64 v[154:155], v[212:213], 0, s[60:61]
	s_mov_b32 m0, s46
	s_nop 0
	global_load_lds_dwordx4 v[154:155], off
	v_lshl_add_u64 v[154:155], v[214:215], 0, s[60:61]
	s_mov_b32 m0, s47
	s_nop 0
	global_load_lds_dwordx4 v[154:155], off
	s_waitcnt vmcnt(8)
	s_waitcnt lgkmcnt(0)
	s_barrier
	s_waitcnt lgkmcnt(0)
	v_mfma_f32_16x16x32_bf16 v[0:3], v[24:27], v[202:205], v[0:3]
	v_mfma_f32_16x16x32_bf16 v[4:7], v[112:115], v[202:205], v[4:7]
	v_mfma_f32_16x16x32_bf16 v[134:137], v[24:27], v[178:181], v[134:137]
	v_mfma_f32_16x16x32_bf16 v[140:143], v[112:115], v[178:181], v[140:143]
	v_mfma_f32_16x16x32_bf16 v[144:147], v[24:27], v[186:189], v[144:147]
	v_mfma_f32_16x16x32_bf16 v[158:161], v[112:115], v[186:189], v[158:161]
	v_mfma_f32_16x16x32_bf16 v[162:165], v[24:27], v[194:197], v[162:165]
	v_mfma_f32_16x16x32_bf16 v[166:169], v[112:115], v[194:197], v[166:169]
	v_mfma_f32_16x16x32_bf16 v[0:3], v[28:31], v[218:221], v[0:3]
	v_mfma_f32_16x16x32_bf16 v[4:7], v[116:119], v[218:221], v[4:7]
	v_mfma_f32_16x16x32_bf16 v[134:137], v[28:31], v[182:185], v[134:137]
	v_mfma_f32_16x16x32_bf16 v[140:143], v[116:119], v[182:185], v[140:143]
	v_mfma_f32_16x16x32_bf16 v[144:147], v[28:31], v[190:193], v[144:147]
	v_mfma_f32_16x16x32_bf16 v[158:161], v[116:119], v[190:193], v[158:161]
	v_mfma_f32_16x16x32_bf16 v[162:165], v[28:31], v[198:201], v[162:165]
	v_mfma_f32_16x16x32_bf16 v[166:169], v[116:119], v[198:201], v[166:169]
	v_mfma_f32_16x16x32_bf16 v[8:11], v[120:123], v[178:181], v[8:11]
	v_mfma_f32_16x16x32_bf16 v[12:15], v[170:173], v[178:181], v[12:15]
	v_mfma_f32_16x16x32_bf16 v[24:27], v[120:123], v[186:189], v[60:63]
	v_mfma_f32_16x16x32_bf16 v[28:31], v[170:173], v[186:189], v[100:103]
	v_mfma_f32_16x16x32_bf16 v[60:63], v[120:123], v[194:197], v[104:107]
	v_mfma_f32_16x16x32_bf16 v[100:103], v[170:173], v[194:197], v[108:111]
	v_mfma_f32_16x16x32_bf16 v[16:19], v[120:123], v[202:205], v[16:19]
	v_mfma_f32_16x16x32_bf16 v[20:23], v[170:173], v[202:205], v[20:23]
	v_mfma_f32_16x16x32_bf16 v[8:11], v[124:127], v[182:185], v[8:11]
	v_mfma_f32_16x16x32_bf16 v[12:15], v[174:177], v[182:185], v[12:15]
	v_mfma_f32_16x16x32_bf16 v[24:27], v[124:127], v[190:193], v[24:27]
	v_mfma_f32_16x16x32_bf16 v[28:31], v[174:177], v[190:193], v[28:31]
	v_mfma_f32_16x16x32_bf16 v[60:63], v[124:127], v[198:201], v[60:63]
	v_mfma_f32_16x16x32_bf16 v[100:103], v[174:177], v[198:201], v[100:103]
	v_mfma_f32_16x16x32_bf16 v[16:19], v[124:127], v[218:221], v[16:19]
	v_mfma_f32_16x16x32_bf16 v[20:23], v[174:177], v[218:221], v[20:23]
	s_barrier
	ds_read_b128 v[104:107], v150
	ds_read_b128 v[108:111], v150 offset:1024
	ds_read_b128 v[112:115], v150 offset:2048
	ds_read_b128 v[116:119], v150 offset:3072
	ds_read_b128 v[120:123], v151
	ds_read_b128 v[124:127], v151 offset:1024
	ds_read_b128 v[170:173], v151 offset:2048
	ds_read_b128 v[174:177], v151 offset:3072
	s_add_u32 s24, s24, 0x10180
	s_addc_u32 s25, s25, 0
	s_mov_b32 m0, s54
	v_lshl_add_u64 v[154:155], s[24:25], 0, v[132:133]
	ds_read_b128 v[178:181], v139
	ds_read_b128 v[182:185], v139 offset:1024
	ds_read_b128 v[186:189], v139 offset:2048
	ds_read_b128 v[190:193], v139 offset:3072
	ds_read_b128 v[194:197], v139 offset:4096
	ds_read_b128 v[198:201], v139 offset:5120
	ds_read_b128 v[202:205], v139 offset:6144
	ds_read_b128 v[218:221], v139 offset:7168
	global_load_lds_dwordx4 v[154:155], off
	v_lshl_add_u64 v[154:155], s[24:25], 0, v[130:131]
	s_mov_b32 m0, s17
	s_nop 0
	global_load_lds_dwordx4 v[154:155], off
	s_waitcnt vmcnt(8)
	s_waitcnt lgkmcnt(0)
	s_barrier
	s_waitcnt lgkmcnt(0)
	v_mfma_f32_16x16x32_bf16 v[64:67], v[104:107], v[178:181], v[64:67]
	v_mfma_f32_16x16x32_bf16 v[68:71], v[112:115], v[178:181], v[68:71]
	v_mfma_f32_16x16x32_bf16 v[72:75], v[104:107], v[186:189], v[72:75]
	v_mfma_f32_16x16x32_bf16 v[76:79], v[112:115], v[186:189], v[76:79]
	v_mfma_f32_16x16x32_bf16 v[80:83], v[104:107], v[194:197], v[80:83]
	v_mfma_f32_16x16x32_bf16 v[84:87], v[112:115], v[194:197], v[84:87]
	v_mfma_f32_16x16x32_bf16 v[88:91], v[104:107], v[202:205], v[88:91]
	v_mfma_f32_16x16x32_bf16 v[92:95], v[112:115], v[202:205], v[92:95]
	v_mfma_f32_16x16x32_bf16 v[64:67], v[108:111], v[182:185], v[64:67]
	v_mfma_f32_16x16x32_bf16 v[68:71], v[116:119], v[182:185], v[68:71]
	v_mfma_f32_16x16x32_bf16 v[72:75], v[108:111], v[190:193], v[72:75]
	v_mfma_f32_16x16x32_bf16 v[76:79], v[116:119], v[190:193], v[76:79]
	v_mfma_f32_16x16x32_bf16 v[80:83], v[108:111], v[198:201], v[80:83]
	v_mfma_f32_16x16x32_bf16 v[84:87], v[116:119], v[198:201], v[84:87]
	v_mfma_f32_16x16x32_bf16 v[88:91], v[108:111], v[218:221], v[88:91]
	v_mfma_f32_16x16x32_bf16 v[92:95], v[116:119], v[218:221], v[92:95]
	v_mfma_f32_16x16x32_bf16 v[32:35], v[170:173], v[178:181], v[32:35]
	v_mfma_f32_16x16x32_bf16 v[36:39], v[120:123], v[186:189], v[36:39]
	v_mfma_f32_16x16x32_bf16 v[40:43], v[170:173], v[186:189], v[40:43]
	v_mfma_f32_16x16x32_bf16 v[44:47], v[120:123], v[194:197], v[44:47]
	v_mfma_f32_16x16x32_bf16 v[48:51], v[170:173], v[194:197], v[48:51]
	v_mfma_f32_16x16x32_bf16 v[52:55], v[120:123], v[202:205], v[52:55]
	v_mfma_f32_16x16x32_bf16 v[56:59], v[170:173], v[202:205], v[56:59]
	v_mfma_f32_16x16x32_bf16 v[96:99], v[120:123], v[178:181], v[96:99]
	v_mfma_f32_16x16x32_bf16 v[32:35], v[174:177], v[182:185], v[32:35]
	v_mfma_f32_16x16x32_bf16 v[36:39], v[124:127], v[190:193], v[36:39]
	v_mfma_f32_16x16x32_bf16 v[40:43], v[174:177], v[190:193], v[40:43]
	v_mfma_f32_16x16x32_bf16 v[44:47], v[124:127], v[198:201], v[44:47]
	v_mfma_f32_16x16x32_bf16 v[48:51], v[174:177], v[198:201], v[48:51]
	v_mfma_f32_16x16x32_bf16 v[52:55], v[124:127], v[218:221], v[52:55]
	v_mfma_f32_16x16x32_bf16 v[56:59], v[174:177], v[218:221], v[56:59]
	v_mfma_f32_16x16x32_bf16 v[222:225], v[124:127], v[182:185], v[96:99]
	s_barrier
	s_mov_b32 m0, s52
	v_lshl_add_u64 v[154:155], s[30:31], 0, v[148:149]
	s_add_u32 s24, s30, 0x10000
	ds_read_b128 v[96:99], v139 offset:16384
	ds_read_b128 v[178:181], v139 offset:17408
	ds_read_b128 v[182:185], v139 offset:18432
	ds_read_b128 v[186:189], v139 offset:19456
	ds_read_b128 v[190:193], v139 offset:20480
	ds_read_b128 v[194:197], v139 offset:21504
	ds_read_b128 v[198:201], v139 offset:22528
	ds_read_b128 v[202:205], v139 offset:23552
	global_load_lds_dwordx4 v[154:155], off
	v_lshl_add_u64 v[156:157], s[30:31], 0, v[128:129]
	s_mov_b32 m0, s19
	s_addc_u32 s25, s31, 0
	global_load_lds_dwordx4 v[156:157], off
	v_lshl_add_u64 v[212:213], s[24:25], 0, v[148:149]
	s_mov_b32 m0, s50
	v_lshl_add_u64 v[214:215], s[34:35], 0, v[130:131]
	global_load_lds_dwordx4 v[212:213], off
	v_lshl_add_u64 v[212:213], s[24:25], 0, v[128:129]
	s_mov_b32 m0, s51
	s_nop 0
	global_load_lds_dwordx4 v[212:213], off
	v_lshl_add_u64 v[212:213], s[34:35], 0, v[132:133]
	s_mov_b32 m0, s40
	s_nop 0
	global_load_lds_dwordx4 v[212:213], off
	s_mov_b32 m0, s41
	s_nop 0
	global_load_lds_dwordx4 v[214:215], off
	s_waitcnt vmcnt(8)
	s_waitcnt lgkmcnt(0)
	s_barrier
	s_waitcnt lgkmcnt(0)
	v_mfma_f32_16x16x32_bf16 v[0:3], v[104:107], v[198:201], v[0:3]
	v_mfma_f32_16x16x32_bf16 v[4:7], v[112:115], v[198:201], v[4:7]
	v_mfma_f32_16x16x32_bf16 v[134:137], v[104:107], v[96:99], v[134:137]
	v_mfma_f32_16x16x32_bf16 v[140:143], v[112:115], v[96:99], v[140:143]
	v_mfma_f32_16x16x32_bf16 v[144:147], v[104:107], v[182:185], v[144:147]
	v_mfma_f32_16x16x32_bf16 v[158:161], v[112:115], v[182:185], v[158:161]
	v_mfma_f32_16x16x32_bf16 v[162:165], v[104:107], v[190:193], v[162:165]
	v_mfma_f32_16x16x32_bf16 v[166:169], v[112:115], v[190:193], v[166:169]
	v_mfma_f32_16x16x32_bf16 v[0:3], v[108:111], v[202:205], v[0:3]
	v_mfma_f32_16x16x32_bf16 v[4:7], v[116:119], v[202:205], v[4:7]
	v_mfma_f32_16x16x32_bf16 v[134:137], v[108:111], v[178:181], v[134:137]
	v_mfma_f32_16x16x32_bf16 v[140:143], v[116:119], v[178:181], v[140:143]
	v_mfma_f32_16x16x32_bf16 v[144:147], v[108:111], v[186:189], v[144:147]
	v_mfma_f32_16x16x32_bf16 v[158:161], v[116:119], v[186:189], v[158:161]
	v_mfma_f32_16x16x32_bf16 v[162:165], v[108:111], v[194:197], v[162:165]
	v_mfma_f32_16x16x32_bf16 v[166:169], v[116:119], v[194:197], v[166:169]
	v_mfma_f32_16x16x32_bf16 v[8:11], v[120:123], v[96:99], v[8:11]
	v_mfma_f32_16x16x32_bf16 v[12:15], v[170:173], v[96:99], v[12:15]
	v_mfma_f32_16x16x32_bf16 v[24:27], v[120:123], v[182:185], v[24:27]
	v_mfma_f32_16x16x32_bf16 v[28:31], v[170:173], v[182:185], v[28:31]
	v_mfma_f32_16x16x32_bf16 v[60:63], v[120:123], v[190:193], v[60:63]
	v_mfma_f32_16x16x32_bf16 v[16:19], v[120:123], v[198:201], v[16:19]
	v_mfma_f32_16x16x32_bf16 v[8:11], v[124:127], v[178:181], v[8:11]
	v_mfma_f32_16x16x32_bf16 v[12:15], v[174:177], v[178:181], v[12:15]
	v_mfma_f32_16x16x32_bf16 v[24:27], v[124:127], v[186:189], v[24:27]
	v_mfma_f32_16x16x32_bf16 v[28:31], v[174:177], v[186:189], v[28:31]
	v_mfma_f32_16x16x32_bf16 v[178:181], v[124:127], v[194:197], v[60:63]
	v_mfma_f32_16x16x32_bf16 v[60:63], v[170:173], v[190:193], v[100:103]
	v_mfma_f32_16x16x32_bf16 v[186:189], v[124:127], v[202:205], v[16:19]
	v_mfma_f32_16x16x32_bf16 v[16:19], v[170:173], v[198:201], v[20:23]
	v_mfma_f32_16x16x32_bf16 v[182:185], v[174:177], v[194:197], v[60:63]
	v_mfma_f32_16x16x32_bf16 v[170:173], v[174:177], v[202:205], v[16:19]
	s_barrier
	s_nop 1
	ds_read_b128 v[60:63], v152
	ds_read_b128 v[174:177], v152 offset:1024
	ds_read_b128 v[190:193], v152 offset:2048
	ds_read_b128 v[194:197], v152 offset:3072
	ds_read_b128 v[198:201], v153
	ds_read_b128 v[202:205], v153 offset:1024
	ds_read_b128 v[218:221], v153 offset:2048
	ds_read_b128 v[226:229], v153 offset:3072
	s_add_u32 s24, s34, 0x10000
	s_addc_u32 s25, s35, 0
	s_mov_b32 m0, s42
	v_lshl_add_u64 v[96:97], s[24:25], 0, v[132:133]
	ds_read_b128 v[16:19], v139 offset:32768
	ds_read_b128 v[20:23], v139 offset:33792
	ds_read_b128 v[108:111], v139 offset:34816
	ds_read_b128 v[230:233], v139 offset:35840
	ds_read_b128 v[234:237], v139 offset:36864
	ds_read_b128 v[238:241], v139 offset:37888
	ds_read_b128 v[242:245], v139 offset:38912
	ds_read_b128 v[246:249], v139 offset:39936
	global_load_lds_dwordx4 v[96:97], off
	v_lshl_add_u64 v[96:97], s[24:25], 0, v[130:131]
	s_mov_b32 m0, s43
	s_nop 0
	global_load_lds_dwordx4 v[96:97], off
	s_waitcnt vmcnt(8)
	s_waitcnt lgkmcnt(0)
	s_barrier
	s_waitcnt lgkmcnt(0)
	v_mfma_f32_16x16x32_bf16 v[64:67], v[60:63], v[16:19], v[64:67]
	v_mfma_f32_16x16x32_bf16 v[112:115], v[174:177], v[20:23], v[64:67]
	v_mfma_f32_16x16x32_bf16 v[64:67], v[190:193], v[16:19], v[68:71]
	v_mfma_f32_16x16x32_bf16 v[116:119], v[194:197], v[20:23], v[64:67]
	v_mfma_f32_16x16x32_bf16 v[64:67], v[60:63], v[108:111], v[72:75]
	v_mfma_f32_16x16x32_bf16 v[96:99], v[174:177], v[230:233], v[64:67]
	v_mfma_f32_16x16x32_bf16 v[64:67], v[190:193], v[108:111], v[76:79]
	v_mfma_f32_16x16x32_bf16 v[100:103], v[194:197], v[230:233], v[64:67]
	v_mfma_f32_16x16x32_bf16 v[64:67], v[60:63], v[234:237], v[80:83]
	v_mfma_f32_16x16x32_bf16 v[80:83], v[174:177], v[238:241], v[64:67]
	v_mfma_f32_16x16x32_bf16 v[64:67], v[190:193], v[234:237], v[84:87]
	v_mfma_f32_16x16x32_bf16 v[84:87], v[194:197], v[238:241], v[64:67]
	v_mfma_f32_16x16x32_bf16 v[64:67], v[60:63], v[242:245], v[88:91]
	v_mfma_f32_16x16x32_bf16 v[68:71], v[190:193], v[242:245], v[92:95]
	v_mfma_f32_16x16x32_bf16 v[64:67], v[174:177], v[246:249], v[64:67]
	v_mfma_f32_16x16x32_bf16 v[68:71], v[194:197], v[246:249], v[68:71]
	v_mfma_f32_16x16x32_bf16 v[72:75], v[198:201], v[16:19], v[222:225]
	v_mfma_f32_16x16x32_bf16 v[16:19], v[218:221], v[16:19], v[32:35]
	v_mfma_f32_16x16x32_bf16 v[124:127], v[226:229], v[20:23], v[16:19]
	v_mfma_f32_16x16x32_bf16 v[16:19], v[198:201], v[108:111], v[36:39]
	v_mfma_f32_16x16x32_bf16 v[104:107], v[202:205], v[230:233], v[16:19]
	v_mfma_f32_16x16x32_bf16 v[16:19], v[218:221], v[108:111], v[40:43]
	v_mfma_f32_16x16x32_bf16 v[108:111], v[226:229], v[230:233], v[16:19]
	v_mfma_f32_16x16x32_bf16 v[16:19], v[198:201], v[234:237], v[44:47]
	v_mfma_f32_16x16x32_bf16 v[88:91], v[202:205], v[238:241], v[16:19]
	v_mfma_f32_16x16x32_bf16 v[16:19], v[218:221], v[234:237], v[48:51]
	v_mfma_f32_16x16x32_bf16 v[92:95], v[226:229], v[238:241], v[16:19]
	v_mfma_f32_16x16x32_bf16 v[16:19], v[198:201], v[242:245], v[52:55]
	v_mfma_f32_16x16x32_bf16 v[120:123], v[202:205], v[20:23], v[72:75]
	v_mfma_f32_16x16x32_bf16 v[72:75], v[202:205], v[246:249], v[16:19]
	v_mfma_f32_16x16x32_bf16 v[16:19], v[218:221], v[242:245], v[56:59]
	v_mfma_f32_16x16x32_bf16 v[76:79], v[226:229], v[246:249], v[16:19]
	s_barrier
	s_mov_b32 m0, s55
	s_nop 4
	v_lshl_add_u64 v[16:17], v[154:155], 0, s[28:29]
	s_add_u32 s24, s30, 0x10080
	ds_read_b128 v[40:43], v139 offset:49152
	ds_read_b128 v[44:47], v139 offset:50176
	ds_read_b128 v[222:225], v139 offset:51200
	ds_read_b128 v[230:233], v139 offset:52224
	ds_read_b128 v[234:237], v139 offset:53248
	ds_read_b128 v[238:241], v139 offset:54272
	ds_read_b128 v[242:245], v139 offset:55296
	ds_read_b128 v[246:249], v139 offset:56320
	global_load_lds_dwordx4 v[16:17], off
	v_lshl_add_u64 v[16:17], v[156:157], 0, s[28:29]
	s_mov_b32 m0, s53
	s_addc_u32 s25, s31, 0
	global_load_lds_dwordx4 v[16:17], off
	v_lshl_add_u64 v[16:17], s[24:25], 0, v[148:149]
	s_mov_b32 m0, s26
	s_nop 0
	global_load_lds_dwordx4 v[16:17], off
	v_lshl_add_u64 v[16:17], s[24:25], 0, v[128:129]
	s_mov_b32 m0, s27
	s_nop 0
	global_load_lds_dwordx4 v[16:17], off
	v_lshl_add_u64 v[16:17], v[212:213], 0, s[28:29]
	s_mov_b32 m0, s46
	s_nop 0
	global_load_lds_dwordx4 v[16:17], off
	v_lshl_add_u64 v[16:17], v[214:215], 0, s[28:29]
	s_mov_b32 m0, s47
	s_nop 0
	global_load_lds_dwordx4 v[16:17], off
	s_waitcnt vmcnt(8)
	s_waitcnt lgkmcnt(0)
	s_barrier
	s_waitcnt lgkmcnt(0)
	v_mfma_f32_16x16x32_bf16 v[16:19], v[60:63], v[40:43], v[134:137]
	v_mfma_f32_16x16x32_bf16 v[48:51], v[174:177], v[44:47], v[16:19]
	v_mfma_f32_16x16x32_bf16 v[16:19], v[190:193], v[40:43], v[140:143]
	v_mfma_f32_16x16x32_bf16 v[52:55], v[194:197], v[44:47], v[16:19]
	v_mfma_f32_16x16x32_bf16 v[16:19], v[60:63], v[222:225], v[144:147]
	v_mfma_f32_16x16x32_bf16 v[32:35], v[174:177], v[230:233], v[16:19]
	v_mfma_f32_16x16x32_bf16 v[16:19], v[190:193], v[222:225], v[158:161]
	v_mfma_f32_16x16x32_bf16 v[36:39], v[194:197], v[230:233], v[16:19]
	v_mfma_f32_16x16x32_bf16 v[16:19], v[60:63], v[234:237], v[162:165]
	v_mfma_f32_16x16x32_bf16 v[20:23], v[190:193], v[234:237], v[166:169]
	v_mfma_f32_16x16x32_bf16 v[0:3], v[60:63], v[242:245], v[0:3]
	v_mfma_f32_16x16x32_bf16 v[4:7], v[190:193], v[242:245], v[4:7]
	v_mfma_f32_16x16x32_bf16 v[16:19], v[174:177], v[238:241], v[16:19]
	v_mfma_f32_16x16x32_bf16 v[20:23], v[194:197], v[238:241], v[20:23]
	v_mfma_f32_16x16x32_bf16 v[0:3], v[174:177], v[246:249], v[0:3]
	v_mfma_f32_16x16x32_bf16 v[4:7], v[194:197], v[246:249], v[4:7]
	v_mfma_f32_16x16x32_bf16 v[8:11], v[198:201], v[40:43], v[8:11]
	v_mfma_f32_16x16x32_bf16 v[56:59], v[202:205], v[44:47], v[8:11]
	v_mfma_f32_16x16x32_bf16 v[8:11], v[218:221], v[40:43], v[12:15]
	v_mfma_f32_16x16x32_bf16 v[60:63], v[226:229], v[44:47], v[8:11]
	v_mfma_f32_16x16x32_bf16 v[8:11], v[198:201], v[222:225], v[24:27]
	v_mfma_f32_16x16x32_bf16 v[40:43], v[202:205], v[230:233], v[8:11]
	v_mfma_f32_16x16x32_bf16 v[8:11], v[218:221], v[222:225], v[28:31]
	v_mfma_f32_16x16x32_bf16 v[44:47], v[226:229], v[230:233], v[8:11]
	v_mfma_f32_16x16x32_bf16 v[8:11], v[198:201], v[234:237], v[178:181]
	v_mfma_f32_16x16x32_bf16 v[24:27], v[202:205], v[238:241], v[8:11]
	v_mfma_f32_16x16x32_bf16 v[8:11], v[218:221], v[234:237], v[182:185]
	v_mfma_f32_16x16x32_bf16 v[28:31], v[226:229], v[238:241], v[8:11]
	v_mfma_f32_16x16x32_bf16 v[8:11], v[198:201], v[242:245], v[186:189]
	v_mfma_f32_16x16x32_bf16 v[12:15], v[218:221], v[242:245], v[170:173]
	v_mfma_f32_16x16x32_bf16 v[8:11], v[202:205], v[246:249], v[8:11]
	v_mfma_f32_16x16x32_bf16 v[12:15], v[226:229], v[246:249], v[12:15]
	s_barrier
	s_andn2_b64 vcc, exec, s[12:13]
	s_cbranch_vccnz .LBB0_873
	s_barrier

.LBB0_1264:
	s_waitcnt vmcnt(0)
	ds_read_b128 v[80:83], v222
	ds_read_b128 v[136:139], v223
	ds_read_b128 v[132:135], v224
	ds_read_b128 v[128:131], v225
	ds_read_b128 v[84:87], v226 offset:4096
	s_add_i32 m0, s33, 0x2000
	s_add_u32 s98, s32, 0x17608000
	s_addc_u32 s99, s100, 0
	global_load_lds_dwordx4 v231, s[98:99]
	s_add_i32 m0, s33, 0x2400
	s_add_u32 s98, s32, 0x17609000
	s_addc_u32 s99, s100, 0
	global_load_lds_dwordx4 v232, s[98:99]
	s_add_i32 m0, s33, 0x2800
	s_add_u32 s98, s32, 0x1760c000
	s_addc_u32 s99, s100, 0
	global_load_lds_dwordx4 v231, s[98:99]
	s_add_i32 m0, s33, 0x2c00
	s_add_u32 s98, s32, 0x1760d000
	s_addc_u32 s99, s100, 0
	global_load_lds_dwordx4 v232, s[98:99]
	s_add_i32 m0, s33, 0x3000
	s_add_u32 s98, s32, 0x15600040
	s_addc_u32 s99, s100, 0
	global_load_lds_dwordx4 v233, s[98:99]
	s_add_i32 m0, s33, 0x3400
	s_add_u32 s98, s32, 0x15700040
	s_addc_u32 s99, s100, 0
	global_load_lds_dwordx4 v233, s[98:99]
	s_add_i32 m0, s33, 0x3800
	s_add_u32 s98, s32, 0x15800040
	s_addc_u32 s99, s100, 0
	global_load_lds_dwordx4 v233, s[98:99]
	s_add_i32 m0, s33, 0x3c00
	s_add_u32 s98, s32, 0x15900040
	s_addc_u32 s99, s100, 0
	global_load_lds_dwordx4 v233, s[98:99]
	s_waitcnt lgkmcnt(0)
	v_mfma_f32_32x32x16_bf16 v[64:79], v[80:83], v[96:99], 0
	v_mfma_f32_32x32x16_bf16 v[64:79], v[136:139], v[100:103], v[64:79]
	v_mfma_f32_32x32x16_bf16 v[64:79], v[132:135], v[104:107], v[64:79]
	v_mfma_f32_32x32x16_bf16 v[64:79], v[128:131], v[108:111], v[64:79]
	v_add_u32_e32 v175, v229, v163
	ds_read2_b32 v[88:89], v175 offset0:0 offset1:1
	ds_read2_b32 v[90:91], v175 offset0:2 offset1:3
	v_readlane_b32 s8, v254, 45
	v_readlane_b32 s9, v254, 46
	s_waitcnt lgkmcnt(0)
	s_nop 6
	v_add_f32_e32 v64, v64, v88
	v_add_u32_e32 v159, v228, v163
	v_cndmask_b32_e64 v88, v216, v64, s[8:9]
	v_readlane_b32 s8, v254, 47
	v_add_f32_e32 v64, v65, v89
	v_readlane_b32 s9, v254, 48
	v_exp_f32_e32 v148, v88
	s_cmp_gt_u32 s12, 13
	v_cndmask_b32_e64 v89, v216, v64, s[8:9]
	v_readlane_b32 s8, v254, 49
	v_add_f32_e32 v64, v66, v90
	v_readlane_b32 s9, v254, 50
	v_add_f32_e32 v66, v67, v91
	v_exp_f32_e32 v177, v89
	v_cndmask_b32_e64 v90, v216, v64, s[8:9]
	v_readlane_b32 s8, v254, 51
	v_readlane_b32 s9, v254, 52
	ds_read2_b32 v[64:65], v175 offset0:4 offset1:5
	v_cndmask_b32_e64 v91, v216, v66, s[8:9]
	ds_read2_b32 v[66:67], v175 offset0:6 offset1:7
	v_exp_f32_e32 v179, v90
	s_waitcnt lgkmcnt(0)
	v_add_f32_e32 v64, v68, v64
	v_add_f32_e32 v65, v69, v65
	v_cndmask_b32_e64 v64, v216, v64, s[20:21]
	v_add_f32_e32 v66, v70, v66
	v_add_f32_e32 v67, v71, v67
	v_cndmask_b32_e64 v65, v216, v65, s[22:23]
	v_cndmask_b32_e64 v66, v216, v66, s[24:25]
	v_cndmask_b32_e64 v67, v216, v67, s[26:27]
	v_exp_f32_e32 v202, v91
	v_exp_f32_e32 v203, v64
	v_exp_f32_e32 v204, v65
	v_exp_f32_e32 v205, v66
	v_exp_f32_e32 v230, v67
	v_cvt_pk_bf16_f32 v140, v148, v177
	v_cvt_pk_bf16_f32 v141, v179, v202
	v_cvt_pk_bf16_f32 v142, v203, v204
	v_cvt_pk_bf16_f32 v143, v205, v230
	ds_read2_b32 v[68:69], v175 offset0:16 offset1:17
	s_nop 0
	v_mfma_f32_32x32x16_bf16 v[32:47], v[84:87], v[140:143], v[32:47]
	ds_read_b128 v[154:157], v226 offset:6144
	ds_read_b128 v[64:67], v227 offset:4096
	ds_read2_b32 v[70:71], v175 offset0:18 offset1:19
	s_waitcnt lgkmcnt(0)
	v_add_f32_e32 v68, v72, v68
	v_cndmask_b32_e64 v72, v216, v68, s[6:7]
	v_add_f32_e32 v68, v73, v69
	v_cndmask_b32_e64 v73, v216, v68, s[30:31]
	v_mfma_f32_32x32x16_bf16 v[80:95], v[80:83], v[112:115], 0
	v_add_f32_e32 v68, v74, v70
	v_cndmask_b32_e64 v150, v216, v68, s[34:35]
	ds_read2_b32 v[68:69], v175 offset0:20 offset1:21
	v_add_f32_e32 v70, v75, v71
	v_cndmask_b32_e64 v75, v216, v70, s[36:37]
	v_mfma_f32_32x32x16_bf16 v[80:95], v[136:139], v[116:119], v[80:95]
	s_waitcnt lgkmcnt(0)
	v_add_f32_e32 v68, v76, v68
	v_cndmask_b32_e64 v76, v216, v68, s[38:39]
	v_add_f32_e32 v68, v77, v69
	v_cndmask_b32_e64 v69, v216, v68, s[40:41]
	v_exp_f32_e32 v198, v69
	ds_read2_b32 v[70:71], v175 offset0:22 offset1:23
	v_mfma_f32_32x32x16_bf16 v[80:95], v[132:135], v[120:123], v[80:95]
	v_exp_f32_e32 v74, v72
	v_exp_f32_e32 v72, v73
	v_readlane_b32 s8, v254, 43
	s_waitcnt lgkmcnt(0)
	v_add_f32_e32 v68, v78, v70
	v_cndmask_b32_e64 v77, v216, v68, s[42:43]
	v_add_f32_e32 v68, v79, v71
	v_cndmask_b32_e64 v71, v216, v68, s[44:45]
	v_mfma_f32_32x32x16_bf16 v[80:95], v[128:131], v[124:127], v[80:95]
	v_exp_f32_e32 v78, v76
	v_exp_f32_e32 v76, v77
	v_exp_f32_e32 v200, v71
	v_readlane_b32 s9, v254, 44
	v_exp_f32_e32 v68, v150
	s_nop 6
	ds_read2_b32 v[80:81], v159 offset0:16 offset1:17
	ds_read2_b32 v[82:83], v159 offset0:18 offset1:19
	v_exp_f32_e32 v70, v75
	v_mfma_f32_32x32x16_bf16 v[48:63], v[154:157], v[140:143], v[48:63]
	s_waitcnt lgkmcnt(0)
	v_add_f32_e32 v69, v88, v80
	v_add_f32_e32 v71, v89, v81
	v_add_f32_e32 v73, v90, v82
	v_cndmask_b32_e64 v77, v216, v73, s[48:49]
	ds_read2_b32 v[80:81], v159 offset0:20 offset1:21
	v_add_f32_e32 v73, v91, v83
	v_cndmask_b32_e64 v79, v216, v73, s[50:51]
	ds_read2_b32 v[82:83], v159 offset0:22 offset1:23
	s_waitcnt lgkmcnt(0)
	v_add_f32_e32 v73, v92, v80
	v_cndmask_b32_e64 v80, v216, v73, s[52:53]
	v_add_f32_e32 v73, v93, v81
	v_cndmask_b32_e64 v84, v216, v73, s[54:55]
	v_add_f32_e32 v73, v94, v82
	v_cndmask_b32_e64 v85, v216, v73, s[56:57]
	v_add_f32_e32 v73, v95, v83
	v_cndmask_b32_e64 v69, v216, v69, s[8:9]
	v_cndmask_b32_e64 v71, v216, v71, s[46:47]
	v_cndmask_b32_e64 v86, v216, v73, s[58:59]
	v_exp_f32_e32 v75, v69
	v_exp_f32_e32 v73, v71
	v_exp_f32_e32 v69, v77
	v_exp_f32_e32 v71, v79
	v_exp_f32_e32 v79, v80
	v_exp_f32_e32 v199, v84
	v_exp_f32_e32 v77, v85
	v_exp_f32_e32 v201, v86
	v_cvt_pk_bf16_f32 v80, v74, v72
	v_cvt_pk_bf16_f32 v81, v68, v70
	v_cvt_pk_bf16_f32 v82, v78, v198
	v_cvt_pk_bf16_f32 v83, v76, v200
	v_cvt_pk_bf16_f32 v154, v75, v73
	v_cvt_pk_bf16_f32 v155, v69, v71
	v_cvt_pk_bf16_f32 v156, v79, v199
	v_cvt_pk_bf16_f32 v157, v77, v201
	v_mfma_f32_32x32x16_bf16 v[32:47], v[64:67], v[80:83], v[32:47]
	s_cselect_b64 s[8:9], -1, 0
	s_and_b64 vcc, exec, s[8:9]
	v_mfma_f32_32x32x16_bf16 v[0:15], v[64:67], v[154:157], v[0:15]
	ds_read_b128 v[64:67], v227 offset:6144
	s_waitcnt vmcnt(0)
	ds_read_b128 v[140:143], v222 offset:8192
	s_waitcnt lgkmcnt(0)
	v_mfma_f32_32x32x16_bf16 v[48:63], v[64:67], v[80:83], v[48:63]
	ds_read_b128 v[136:139], v223 offset:8192
	ds_read_b128 v[128:131], v224 offset:8192
	ds_read_b128 v[132:135], v225 offset:8192
	ds_read_b128 v[92:95], v226 offset:12288
	ds_read_b128 v[88:91], v226 offset:14336
	ds_read_b128 v[84:87], v227 offset:12288
	ds_read_b128 v[80:83], v227 offset:14336
	v_mfma_f32_32x32x16_bf16 v[16:31], v[64:67], v[154:157], v[16:31]
	s_cbranch_vccnz .LBB0_1263
	s_mov_b32 m0, s33
	s_add_u32 s98, s32, 0x17610000
	s_addc_u32 s99, s100, 0
	global_load_lds_dwordx4 v231, s[98:99]
	s_add_i32 m0, s33, 0x400
	s_add_u32 s98, s32, 0x17611000
	s_addc_u32 s99, s100, 0
	global_load_lds_dwordx4 v232, s[98:99]
	s_add_i32 m0, s33, 0x800
	s_add_u32 s98, s32, 0x17614000
	s_addc_u32 s99, s100, 0
	global_load_lds_dwordx4 v231, s[98:99]
	s_add_i32 m0, s33, 0xc00
	s_add_u32 s98, s32, 0x17615000
	s_addc_u32 s99, s100, 0
	global_load_lds_dwordx4 v232, s[98:99]
	s_add_i32 m0, s33, 0x1000
	s_add_u32 s98, s32, 0x15600080
	s_addc_u32 s99, s100, 0
	global_load_lds_dwordx4 v233, s[98:99]
	s_add_i32 m0, s33, 0x1400
	s_add_u32 s98, s32, 0x15700080
	s_addc_u32 s99, s100, 0
	global_load_lds_dwordx4 v233, s[98:99]
	s_add_i32 m0, s33, 0x1800
	s_add_u32 s98, s32, 0x15800080
	s_addc_u32 s99, s100, 0
	global_load_lds_dwordx4 v233, s[98:99]
	s_add_i32 m0, s33, 0x1c00
	s_add_u32 s98, s32, 0x15900080
	s_addc_u32 s99, s100, 0
	global_load_lds_dwordx4 v233, s[98:99]
	s_branch .LBB0_1263
